# GEMM2/4 residual epilogue from registers (half-row loads, packed adds, cndmask-dpp exchange, whole-row stores)
# speedup vs baseline: 1.0134x; 1.0005x over previous
; #define LAS __attribute__((address_space(3)))
; __device__ __forceinline__ float bf_lo(unsigned w) { return __uint_as_float(w << 16); }
;     __device__ __forceinline__ void operator()(const f32x4 (&acc)[2][2][4][2], const Unit& u, int wr, int wc, int fr, int fq) const {
;         const int ln = fr + 16 * fq, rr = ln >> 3, cc = ln & 7; const int colw = u.pn * BM + 64 * wc;
;         LAS unsigned char* sl = stg + (wr * 4 + wc) * EPI_STG_SLICE;
; #pragma unroll
;         for (int ai = 0; ai < 2; ++ai) {
;             float qs[4];
; #pragma unroll
;             for (int mh = 0; mh < 2; ++mh) {
;             u32x4 bs[4][2];
; #pragma unroll
;             for (int m = 2 * mh; m < 2 * mh + 2; ++m) { const int rowb = u.pm * BM + ai * HALF + wr * 64 + m * 16;
; #pragma unroll
;                 for (int i = 0; i < 2; ++i) bs[m][i] = *(const u32x4*)(xb + (size_t)(rowb + rr + 8 * i) * DM + colw + cc * 8); }
; #pragma unroll
;             for (int m = 2 * mh; m < 2 * mh + 2; ++m) {
;                 const int rowb = u.pm * BM + ai * HALF + wr * 64 + m * 16; float q = 0.f;
; #pragma unroll
;                 for (int i = 0; i < 2; ++i) *(LAS u32x4*)(sl + (rr + 8 * i) * 144 + cc * 16) = bs[m][i];
; #pragma unroll
;                 for (int bj = 0; bj < 2; ++bj) {
;                     const u32x4 b4 = *(const LAS u32x4*)(sl + fr * 144 + bj * 64 + fq * 16);
;                     const f32x4 a0 = acc[ai][bj][m][0], a1 = acc[ai][bj][m][1];
;                     const float o0 = bf_lo(b4.x) + a0[0], o1 = bf_hi(b4.x) + a0[1], o2 = bf_lo(b4.y) + a0[2], o3 = bf_hi(b4.y) + a0[3];
;                     const float o4 = bf_lo(b4.z) + a1[0], o5 = bf_hi(b4.z) + a1[1], o6 = bf_lo(b4.w) + a1[2], o7 = bf_hi(b4.w) + a1[3];
;                     q += ((o0 * o0 + o1 * o1) + (o2 * o2 + o3 * o3)) + ((o4 * o4 + o5 * o5) + (o6 * o6 + o7 * o7));
;                     u32x4 w; w.x = cvt_pk_bf16(o0, o1); w.y = cvt_pk_bf16(o2, o3); w.z = cvt_pk_bf16(o4, o5); w.w = cvt_pk_bf16(o6, o7);
;                     *(LAS u32x4*)(sl + fr * 144 + bj * 64 + fq * 16) = w;
;                 }
; #pragma unroll
;                 for (int i = 0; i < 2; ++i) { const u32x4 qv = *(const LAS u32x4*)(sl + (rr + 8 * i) * 144 + cc * 16);
;                     *(u32x4*)(xb + (size_t)(rowb + rr + 8 * i) * DM + colw + cc * 8) = qv; }
.LBB0_429:
	s_lshl_b32 s2, s2, 8
	s_or_b32 s4, s2, s92
	s_lshl_b32 s2, s3, 8
	s_add_i32 s2, s2, s83
	s_lshl_b32 s7, s2, 11
	s_lshl_b32 s32, s4, 1
	s_add_u32 s7, s7, s32
	s_add_u32 s62, s44, s7
	s_addc_u32 s63, s45, 0
	v_and_b32_e32 v172, 15, v177
	v_bfe_u32 v173, v177, 4, 2
	v_lshlrev_b32_e32 v250, 11, v172
	v_lshl_add_u32 v250, v173, 4, v250
	v_and_b32_e32 v188, 1, v177
	v_and_b32_e32 v189, 14, v177
	v_cmp_eq_u32_e64 s[10:11], 0, v188
	v_cmp_ne_u32_e64 s[98:99], 0, v188
	v_lshlrev_b32_e32 v251, 11, v189
	v_lshl_add_u32 v251, v188, 6, v251
	v_lshl_add_u32 v251, v173, 4, v251
	v_add_u32_e32 v163, 0x800, v251
	s_mov_b32 s64, s62
	s_mov_b32 s65, s63
	global_load_dwordx4 v[206:209], v250, s[64:65]
	global_load_dwordx4 v[210:213], v250, s[64:65] offset:64
	s_add_u32 s64, s62, 0x8000
	s_addc_u32 s65, s63, 0
	global_load_dwordx4 v[214:217], v250, s[64:65]
	global_load_dwordx4 v[218:221], v250, s[64:65] offset:64
	s_add_u32 s64, s62, 0x10000
	s_addc_u32 s65, s63, 0
	global_load_dwordx4 v[222:225], v250, s[64:65]
	global_load_dwordx4 v[226:229], v250, s[64:65] offset:64
	s_add_u32 s64, s62, 0x18000
	s_addc_u32 s65, s63, 0
	global_load_dwordx4 v[230:233], v250, s[64:65]
	global_load_dwordx4 v[234:237], v250, s[64:65] offset:64
	s_add_u32 s64, s62, 0x40000
	s_addc_u32 s65, s63, 0
	global_load_dwordx4 v[238:241], v250, s[64:65]
	global_load_dwordx4 v[242:245], v250, s[64:65] offset:64
	s_add_u32 s64, s62, 0x48000
	s_addc_u32 s65, s63, 0
	global_load_dwordx4 v[246:249], v250, s[64:65]
	global_load_dwordx4 v[198:201], v250, s[64:65] offset:64
	s_add_u32 s64, s62, 0x50000
	s_addc_u32 s65, s63, 0
	global_load_dwordx4 v[202:205], v250, s[64:65]
	global_load_dwordx4 v[130:133], v250, s[64:65] offset:64
	s_add_u32 s64, s62, 0x58000
	s_addc_u32 s65, s63, 0
	global_load_dwordx4 v[134:137], v250, s[64:65]
	global_load_dwordx4 v[164:167], v250, s[64:65] offset:64
	s_waitcnt vmcnt(14)
	v_lshlrev_b32_e32 v172, 16, v206
	v_and_b32_e32 v173, 0xffff0000, v206
	v_pk_add_f32 v[126:127], v[126:127], v[172:173]
	v_lshlrev_b32_e32 v172, 16, v207
	v_and_b32_e32 v173, 0xffff0000, v207
	v_pk_add_f32 v[128:129], v[128:129], v[172:173]
	v_lshlrev_b32_e32 v172, 16, v208
	v_and_b32_e32 v173, 0xffff0000, v208
	v_pk_add_f32 v[122:123], v[122:123], v[172:173]
	v_lshlrev_b32_e32 v172, 16, v209
	v_and_b32_e32 v173, 0xffff0000, v209
	v_pk_add_f32 v[124:125], v[124:125], v[172:173]
	v_mul_f32_e32 v172, v127, v127
	v_mul_f32_e32 v173, v129, v129
	v_mul_f32_e32 v188, v123, v123
	v_mul_f32_e32 v189, v125, v125
	v_fmac_f32_e32 v172, v126, v126
	v_fmac_f32_e32 v173, v128, v128
	v_fmac_f32_e32 v188, v122, v122
	v_fmac_f32_e32 v189, v124, v124
	v_add_f32_e32 v172, v172, v173
	v_add_f32_e32 v188, v188, v189
	v_add_f32_e32 v172, v172, v188
	v_mov_b32_e32 v168, v172
	v_cvt_pk_bf16_f32 v126, v126, v127
	v_cvt_pk_bf16_f32 v127, v128, v129
	v_cvt_pk_bf16_f32 v128, v122, v123
	v_cvt_pk_bf16_f32 v129, v124, v125
	v_lshlrev_b32_e32 v172, 16, v210
	v_and_b32_e32 v173, 0xffff0000, v210
	v_pk_add_f32 v[118:119], v[118:119], v[172:173]
	v_lshlrev_b32_e32 v172, 16, v211
	v_and_b32_e32 v173, 0xffff0000, v211
	v_pk_add_f32 v[120:121], v[120:121], v[172:173]
	v_lshlrev_b32_e32 v172, 16, v212
	v_and_b32_e32 v173, 0xffff0000, v212
	v_pk_add_f32 v[114:115], v[114:115], v[172:173]
	v_lshlrev_b32_e32 v172, 16, v213
	v_and_b32_e32 v173, 0xffff0000, v213
	v_pk_add_f32 v[116:117], v[116:117], v[172:173]
	v_mul_f32_e32 v172, v119, v119
	v_mul_f32_e32 v173, v121, v121
	v_mul_f32_e32 v188, v115, v115
	v_mul_f32_e32 v189, v117, v117
	v_fmac_f32_e32 v172, v118, v118
	v_fmac_f32_e32 v173, v120, v120
	v_fmac_f32_e32 v188, v114, v114
	v_fmac_f32_e32 v189, v116, v116
	v_add_f32_e32 v172, v172, v173
	v_add_f32_e32 v188, v188, v189
	v_add_f32_e32 v172, v172, v188
	v_add_f32_e32 v168, v168, v172
	v_cvt_pk_bf16_f32 v118, v118, v119
	v_cvt_pk_bf16_f32 v119, v120, v121
	v_cvt_pk_bf16_f32 v120, v114, v115
	v_cvt_pk_bf16_f32 v121, v116, v117
	s_mov_b64 vcc, s[98:99]
	v_cndmask_b32_dpp v122, v126, v118, vcc quad_perm:[1,0,3,2] row_mask:0xf bank_mask:0xf
	v_cndmask_b32_dpp v123, v127, v119, vcc quad_perm:[1,0,3,2] row_mask:0xf bank_mask:0xf
	v_cndmask_b32_dpp v124, v128, v120, vcc quad_perm:[1,0,3,2] row_mask:0xf bank_mask:0xf
	v_cndmask_b32_dpp v125, v129, v121, vcc quad_perm:[1,0,3,2] row_mask:0xf bank_mask:0xf
	s_mov_b64 vcc, s[10:11]
	v_cndmask_b32_dpp v126, v118, v126, vcc quad_perm:[1,0,3,2] row_mask:0xf bank_mask:0xf
	v_cndmask_b32_dpp v127, v119, v127, vcc quad_perm:[1,0,3,2] row_mask:0xf bank_mask:0xf
	v_cndmask_b32_dpp v128, v120, v128, vcc quad_perm:[1,0,3,2] row_mask:0xf bank_mask:0xf
	v_cndmask_b32_dpp v129, v121, v129, vcc quad_perm:[1,0,3,2] row_mask:0xf bank_mask:0xf
	s_mov_b32 s64, s62
	s_mov_b32 s65, s63
	global_store_dwordx4 v251, v[126:129], s[64:65]
	global_store_dwordx4 v163, v[122:125], s[64:65]
	s_waitcnt vmcnt(14)
; #define LAS __attribute__((address_space(3)))
; __device__ __forceinline__ float bf_lo(unsigned w) { return __uint_as_float(w << 16); }
; __device__ __forceinline__ float bf_hi(unsigned w) { return __uint_as_float(w & 0xffff0000u); }
; __device__ __forceinline__ unsigned cvt_pk_bf16(float lo, float hi) { unsigned r; asm volatile("v_cvt_pk_bf16_f32 %0, %1, %2" : "=v"(r) : "v"(lo), "v"(hi)); return r; }
;     __device__ __forceinline__ void operator()(const f32x4 (&acc)[2][2][4][2], const Unit& u, int wr, int wc, int fr, int fq) const {
;     ...
;             for (int m = 2 * mh; m < 2 * mh + 2; ++m) { const int rowb = u.pm * BM + ai * HALF + wr * 64 + m * 16;
; #pragma unroll
;                 for (int i = 0; i < 2; ++i) bs[m][i] = *(const u32x4*)(xb + (size_t)(rowb + rr + 8 * i) * DM + colw + cc * 8); }
; #pragma unroll
;             for (int m = 2 * mh; m < 2 * mh + 2; ++m) {
;                 const int rowb = u.pm * BM + ai * HALF + wr * 64 + m * 16; float q = 0.f;
; #pragma unroll
;                 for (int i = 0; i < 2; ++i) *(LAS u32x4*)(sl + (rr + 8 * i) * 144 + cc * 16) = bs[m][i];
; #pragma unroll
;                 for (int bj = 0; bj < 2; ++bj) {
;                     const u32x4 b4 = *(const LAS u32x4*)(sl + fr * 144 + bj * 64 + fq * 16);
;                     const f32x4 a0 = acc[ai][bj][m][0], a1 = acc[ai][bj][m][1];
;                     const float o0 = bf_lo(b4.x) + a0[0], o1 = bf_hi(b4.x) + a0[1], o2 = bf_lo(b4.y) + a0[2], o3 = bf_hi(b4.y) + a0[3];
;                     const float o4 = bf_lo(b4.z) + a1[0], o5 = bf_hi(b4.z) + a1[1], o6 = bf_lo(b4.w) + a1[2], o7 = bf_hi(b4.w) + a1[3];
;                     q += ((o0 * o0 + o1 * o1) + (o2 * o2 + o3 * o3)) + ((o4 * o4 + o5 * o5) + (o6 * o6 + o7 * o7));
;                     u32x4 w; w.x = cvt_pk_bf16(o0, o1); w.y = cvt_pk_bf16(o2, o3); w.z = cvt_pk_bf16(o4, o5); w.w = cvt_pk_bf16(o6, o7);
;                     *(LAS u32x4*)(sl + fr * 144 + bj * 64 + fq * 16) = w;
;                 }
; #pragma unroll
;                 for (int i = 0; i < 2; ++i) { const u32x4 qv = *(const LAS u32x4*)(sl + (rr + 8 * i) * 144 + cc * 16);
;                     *(u32x4*)(xb + (size_t)(rowb + rr + 8 * i) * DM + colw + cc * 8) = qv; }
	v_lshlrev_b32_e32 v172, 16, v214
	v_and_b32_e32 v173, 0xffff0000, v214
	v_pk_add_f32 v[110:111], v[110:111], v[172:173]
	v_lshlrev_b32_e32 v172, 16, v215
	v_and_b32_e32 v173, 0xffff0000, v215
	v_pk_add_f32 v[112:113], v[112:113], v[172:173]
	v_lshlrev_b32_e32 v172, 16, v216
	v_and_b32_e32 v173, 0xffff0000, v216
	v_pk_add_f32 v[106:107], v[106:107], v[172:173]
	v_lshlrev_b32_e32 v172, 16, v217
	v_and_b32_e32 v173, 0xffff0000, v217
	v_pk_add_f32 v[108:109], v[108:109], v[172:173]
	v_mul_f32_e32 v172, v111, v111
	v_mul_f32_e32 v173, v113, v113
	v_mul_f32_e32 v188, v107, v107
	v_mul_f32_e32 v189, v109, v109
	v_fmac_f32_e32 v172, v110, v110
	v_fmac_f32_e32 v173, v112, v112
	v_fmac_f32_e32 v188, v106, v106
	v_fmac_f32_e32 v189, v108, v108
	v_add_f32_e32 v172, v172, v173
	v_add_f32_e32 v188, v188, v189
	v_add_f32_e32 v172, v172, v188
	v_mov_b32_e32 v169, v172
	v_cvt_pk_bf16_f32 v110, v110, v111
	v_cvt_pk_bf16_f32 v111, v112, v113
	v_cvt_pk_bf16_f32 v112, v106, v107
	v_cvt_pk_bf16_f32 v113, v108, v109
	v_lshlrev_b32_e32 v172, 16, v218
	v_and_b32_e32 v173, 0xffff0000, v218
	v_pk_add_f32 v[102:103], v[102:103], v[172:173]
	v_lshlrev_b32_e32 v172, 16, v219
	v_and_b32_e32 v173, 0xffff0000, v219
	v_pk_add_f32 v[104:105], v[104:105], v[172:173]
	v_lshlrev_b32_e32 v172, 16, v220
	v_and_b32_e32 v173, 0xffff0000, v220
	v_pk_add_f32 v[98:99], v[98:99], v[172:173]
	v_lshlrev_b32_e32 v172, 16, v221
	v_and_b32_e32 v173, 0xffff0000, v221
	v_pk_add_f32 v[100:101], v[100:101], v[172:173]
	v_mul_f32_e32 v172, v103, v103
	v_mul_f32_e32 v173, v105, v105
	v_mul_f32_e32 v188, v99, v99
	v_mul_f32_e32 v189, v101, v101
	v_fmac_f32_e32 v172, v102, v102
	v_fmac_f32_e32 v173, v104, v104
	v_fmac_f32_e32 v188, v98, v98
	v_fmac_f32_e32 v189, v100, v100
	v_add_f32_e32 v172, v172, v173
	v_add_f32_e32 v188, v188, v189
	v_add_f32_e32 v172, v172, v188
	v_add_f32_e32 v169, v169, v172
	v_cvt_pk_bf16_f32 v102, v102, v103
	v_cvt_pk_bf16_f32 v103, v104, v105
	v_cvt_pk_bf16_f32 v104, v98, v99
	v_cvt_pk_bf16_f32 v105, v100, v101
	s_mov_b64 vcc, s[98:99]
	v_cndmask_b32_dpp v106, v110, v102, vcc quad_perm:[1,0,3,2] row_mask:0xf bank_mask:0xf
	v_cndmask_b32_dpp v107, v111, v103, vcc quad_perm:[1,0,3,2] row_mask:0xf bank_mask:0xf
	v_cndmask_b32_dpp v108, v112, v104, vcc quad_perm:[1,0,3,2] row_mask:0xf bank_mask:0xf
	v_cndmask_b32_dpp v109, v113, v105, vcc quad_perm:[1,0,3,2] row_mask:0xf bank_mask:0xf
	s_mov_b64 vcc, s[10:11]
	v_cndmask_b32_dpp v110, v102, v110, vcc quad_perm:[1,0,3,2] row_mask:0xf bank_mask:0xf
	v_cndmask_b32_dpp v111, v103, v111, vcc quad_perm:[1,0,3,2] row_mask:0xf bank_mask:0xf
	v_cndmask_b32_dpp v112, v104, v112, vcc quad_perm:[1,0,3,2] row_mask:0xf bank_mask:0xf
	v_cndmask_b32_dpp v113, v105, v113, vcc quad_perm:[1,0,3,2] row_mask:0xf bank_mask:0xf
	s_add_u32 s64, s62, 0x8000
	s_addc_u32 s65, s63, 0
	global_store_dwordx4 v251, v[110:113], s[64:65]
	global_store_dwordx4 v163, v[106:109], s[64:65]
	s_waitcnt vmcnt(14)
	v_lshlrev_b32_e32 v172, 16, v222
	v_and_b32_e32 v173, 0xffff0000, v222
	v_pk_add_f32 v[94:95], v[94:95], v[172:173]
	v_lshlrev_b32_e32 v172, 16, v223
	v_and_b32_e32 v173, 0xffff0000, v223
	v_pk_add_f32 v[96:97], v[96:97], v[172:173]
	v_lshlrev_b32_e32 v172, 16, v224
	v_and_b32_e32 v173, 0xffff0000, v224
	v_pk_add_f32 v[90:91], v[90:91], v[172:173]
	v_lshlrev_b32_e32 v172, 16, v225
	v_and_b32_e32 v173, 0xffff0000, v225
	v_pk_add_f32 v[92:93], v[92:93], v[172:173]
	v_mul_f32_e32 v172, v95, v95
	v_mul_f32_e32 v173, v97, v97
	v_mul_f32_e32 v188, v91, v91
	v_mul_f32_e32 v189, v93, v93
	v_fmac_f32_e32 v172, v94, v94
	v_fmac_f32_e32 v173, v96, v96
	v_fmac_f32_e32 v188, v90, v90
	v_fmac_f32_e32 v189, v92, v92
	v_add_f32_e32 v172, v172, v173
	v_add_f32_e32 v188, v188, v189
	v_add_f32_e32 v172, v172, v188
	v_mov_b32_e32 v170, v172
	v_cvt_pk_bf16_f32 v94, v94, v95
	v_cvt_pk_bf16_f32 v95, v96, v97
	v_cvt_pk_bf16_f32 v96, v90, v91
	v_cvt_pk_bf16_f32 v97, v92, v93
	v_lshlrev_b32_e32 v172, 16, v226
	v_and_b32_e32 v173, 0xffff0000, v226
	v_pk_add_f32 v[86:87], v[86:87], v[172:173]
	v_lshlrev_b32_e32 v172, 16, v227
	v_and_b32_e32 v173, 0xffff0000, v227
	v_pk_add_f32 v[88:89], v[88:89], v[172:173]
	v_lshlrev_b32_e32 v172, 16, v228
	v_and_b32_e32 v173, 0xffff0000, v228
	v_pk_add_f32 v[82:83], v[82:83], v[172:173]
	v_lshlrev_b32_e32 v172, 16, v229
	v_and_b32_e32 v173, 0xffff0000, v229
	v_pk_add_f32 v[84:85], v[84:85], v[172:173]
	v_mul_f32_e32 v172, v87, v87
	v_mul_f32_e32 v173, v89, v89
	v_mul_f32_e32 v188, v83, v83
	v_mul_f32_e32 v189, v85, v85
	v_fmac_f32_e32 v172, v86, v86
	v_fmac_f32_e32 v173, v88, v88
	v_fmac_f32_e32 v188, v82, v82
	v_fmac_f32_e32 v189, v84, v84
	v_add_f32_e32 v172, v172, v173
	v_add_f32_e32 v188, v188, v189
	v_add_f32_e32 v172, v172, v188
	v_add_f32_e32 v170, v170, v172
	v_cvt_pk_bf16_f32 v86, v86, v87
	v_cvt_pk_bf16_f32 v87, v88, v89
	v_cvt_pk_bf16_f32 v88, v82, v83
	v_cvt_pk_bf16_f32 v89, v84, v85
	s_mov_b64 vcc, s[98:99]
	v_cndmask_b32_dpp v90, v94, v86, vcc quad_perm:[1,0,3,2] row_mask:0xf bank_mask:0xf
	v_cndmask_b32_dpp v91, v95, v87, vcc quad_perm:[1,0,3,2] row_mask:0xf bank_mask:0xf
	v_cndmask_b32_dpp v92, v96, v88, vcc quad_perm:[1,0,3,2] row_mask:0xf bank_mask:0xf
	v_cndmask_b32_dpp v93, v97, v89, vcc quad_perm:[1,0,3,2] row_mask:0xf bank_mask:0xf
	s_mov_b64 vcc, s[10:11]
	v_cndmask_b32_dpp v94, v86, v94, vcc quad_perm:[1,0,3,2] row_mask:0xf bank_mask:0xf
	v_cndmask_b32_dpp v95, v87, v95, vcc quad_perm:[1,0,3,2] row_mask:0xf bank_mask:0xf
	v_cndmask_b32_dpp v96, v88, v96, vcc quad_perm:[1,0,3,2] row_mask:0xf bank_mask:0xf
	v_cndmask_b32_dpp v97, v89, v97, vcc quad_perm:[1,0,3,2] row_mask:0xf bank_mask:0xf
	s_add_u32 s64, s62, 0x10000
	s_addc_u32 s65, s63, 0
	global_store_dwordx4 v251, v[94:97], s[64:65]
	global_store_dwordx4 v163, v[90:93], s[64:65]
	s_waitcnt vmcnt(14)
; #define LAS __attribute__((address_space(3)))
; __device__ __forceinline__ float bf_lo(unsigned w) { return __uint_as_float(w << 16); }
; __device__ __forceinline__ float bf_hi(unsigned w) { return __uint_as_float(w & 0xffff0000u); }
; __device__ __forceinline__ unsigned cvt_pk_bf16(float lo, float hi) { unsigned r; asm volatile("v_cvt_pk_bf16_f32 %0, %1, %2" : "=v"(r) : "v"(lo), "v"(hi)); return r; }
;     __device__ __forceinline__ void operator()(const f32x4 (&acc)[2][2][4][2], const Unit& u, int wr, int wc, int fr, int fq) const {
;     ...
;             for (int m = 2 * mh; m < 2 * mh + 2; ++m) {
;                 const int rowb = u.pm * BM + ai * HALF + wr * 64 + m * 16; float q = 0.f;
; #pragma unroll
;                 for (int i = 0; i < 2; ++i) *(LAS u32x4*)(sl + (rr + 8 * i) * 144 + cc * 16) = bs[m][i];
; #pragma unroll
;                 for (int bj = 0; bj < 2; ++bj) {
;                     const u32x4 b4 = *(const LAS u32x4*)(sl + fr * 144 + bj * 64 + fq * 16);
;                     const f32x4 a0 = acc[ai][bj][m][0], a1 = acc[ai][bj][m][1];
;                     const float o0 = bf_lo(b4.x) + a0[0], o1 = bf_hi(b4.x) + a0[1], o2 = bf_lo(b4.y) + a0[2], o3 = bf_hi(b4.y) + a0[3];
;                     const float o4 = bf_lo(b4.z) + a1[0], o5 = bf_hi(b4.z) + a1[1], o6 = bf_lo(b4.w) + a1[2], o7 = bf_hi(b4.w) + a1[3];
;                     q += ((o0 * o0 + o1 * o1) + (o2 * o2 + o3 * o3)) + ((o4 * o4 + o5 * o5) + (o6 * o6 + o7 * o7));
;                     u32x4 w; w.x = cvt_pk_bf16(o0, o1); w.y = cvt_pk_bf16(o2, o3); w.z = cvt_pk_bf16(o4, o5); w.w = cvt_pk_bf16(o6, o7);
;                     *(LAS u32x4*)(sl + fr * 144 + bj * 64 + fq * 16) = w;
;                 }
; #pragma unroll
;                 for (int i = 0; i < 2; ++i) { const u32x4 qv = *(const LAS u32x4*)(sl + (rr + 8 * i) * 144 + cc * 16);
;                     *(u32x4*)(xb + (size_t)(rowb + rr + 8 * i) * DM + colw + cc * 8) = qv; }
;                 q += __shfl_xor(q, 16); q += __shfl_xor(q, 32); qs[m] = q;
;             }
;             asm volatile("" ::: "memory");
;             }
;             { const float mine = fq == 0 ? qs[0] : (fq == 1 ? qs[1] : (fq == 2 ? qs[2] : qs[3]));
;               __hip_atomic_fetch_add(ssq + (u.pm * BM + ai * HALF + wr * 64 + 16 * fq + fr), (u64)(mine * 16777216.0f), __ATOMIC_RELAXED, __HIP_MEMORY_SCOPE_AGENT); }
	v_lshlrev_b32_e32 v172, 16, v230
	v_and_b32_e32 v173, 0xffff0000, v230
	v_pk_add_f32 v[78:79], v[78:79], v[172:173]
	v_lshlrev_b32_e32 v172, 16, v231
	v_and_b32_e32 v173, 0xffff0000, v231
	v_pk_add_f32 v[80:81], v[80:81], v[172:173]
	v_lshlrev_b32_e32 v172, 16, v232
	v_and_b32_e32 v173, 0xffff0000, v232
	v_pk_add_f32 v[74:75], v[74:75], v[172:173]
	v_lshlrev_b32_e32 v172, 16, v233
	v_and_b32_e32 v173, 0xffff0000, v233
	v_pk_add_f32 v[76:77], v[76:77], v[172:173]
	v_mul_f32_e32 v172, v79, v79
	v_mul_f32_e32 v173, v81, v81
	v_mul_f32_e32 v188, v75, v75
	v_mul_f32_e32 v189, v77, v77
	v_fmac_f32_e32 v172, v78, v78
	v_fmac_f32_e32 v173, v80, v80
	v_fmac_f32_e32 v188, v74, v74
	v_fmac_f32_e32 v189, v76, v76
	v_add_f32_e32 v172, v172, v173
	v_add_f32_e32 v188, v188, v189
	v_add_f32_e32 v172, v172, v188
	v_mov_b32_e32 v171, v172
	v_cvt_pk_bf16_f32 v78, v78, v79
	v_cvt_pk_bf16_f32 v79, v80, v81
	v_cvt_pk_bf16_f32 v80, v74, v75
	v_cvt_pk_bf16_f32 v81, v76, v77
	v_lshlrev_b32_e32 v172, 16, v234
	v_and_b32_e32 v173, 0xffff0000, v234
	v_pk_add_f32 v[70:71], v[70:71], v[172:173]
	v_lshlrev_b32_e32 v172, 16, v235
	v_and_b32_e32 v173, 0xffff0000, v235
	v_pk_add_f32 v[72:73], v[72:73], v[172:173]
	v_lshlrev_b32_e32 v172, 16, v236
	v_and_b32_e32 v173, 0xffff0000, v236
	v_pk_add_f32 v[66:67], v[66:67], v[172:173]
	v_lshlrev_b32_e32 v172, 16, v237
	v_and_b32_e32 v173, 0xffff0000, v237
	v_pk_add_f32 v[68:69], v[68:69], v[172:173]
	v_mul_f32_e32 v172, v71, v71
	v_mul_f32_e32 v173, v73, v73
	v_mul_f32_e32 v188, v67, v67
	v_mul_f32_e32 v189, v69, v69
	v_fmac_f32_e32 v172, v70, v70
	v_fmac_f32_e32 v173, v72, v72
	v_fmac_f32_e32 v188, v66, v66
	v_fmac_f32_e32 v189, v68, v68
	v_add_f32_e32 v172, v172, v173
	v_add_f32_e32 v188, v188, v189
	v_add_f32_e32 v172, v172, v188
	v_add_f32_e32 v171, v171, v172
	v_cvt_pk_bf16_f32 v70, v70, v71
	v_cvt_pk_bf16_f32 v71, v72, v73
	v_cvt_pk_bf16_f32 v72, v66, v67
	v_cvt_pk_bf16_f32 v73, v68, v69
	s_mov_b64 vcc, s[98:99]
	v_cndmask_b32_dpp v74, v78, v70, vcc quad_perm:[1,0,3,2] row_mask:0xf bank_mask:0xf
	v_cndmask_b32_dpp v75, v79, v71, vcc quad_perm:[1,0,3,2] row_mask:0xf bank_mask:0xf
	v_cndmask_b32_dpp v76, v80, v72, vcc quad_perm:[1,0,3,2] row_mask:0xf bank_mask:0xf
	v_cndmask_b32_dpp v77, v81, v73, vcc quad_perm:[1,0,3,2] row_mask:0xf bank_mask:0xf
	s_mov_b64 vcc, s[10:11]
	v_cndmask_b32_dpp v78, v70, v78, vcc quad_perm:[1,0,3,2] row_mask:0xf bank_mask:0xf
	v_cndmask_b32_dpp v79, v71, v79, vcc quad_perm:[1,0,3,2] row_mask:0xf bank_mask:0xf
	v_cndmask_b32_dpp v80, v72, v80, vcc quad_perm:[1,0,3,2] row_mask:0xf bank_mask:0xf
	v_cndmask_b32_dpp v81, v73, v81, vcc quad_perm:[1,0,3,2] row_mask:0xf bank_mask:0xf
	s_add_u32 s64, s62, 0x18000
	s_addc_u32 s65, s63, 0
	global_store_dwordx4 v251, v[78:81], s[64:65]
	global_store_dwordx4 v163, v[74:77], s[64:65]
	v_xor_b32_e32 v172, 16, v177
	v_lshlrev_b32_e32 v172, 2, v172
	v_xor_b32_e32 v173, 32, v177
	v_lshlrev_b32_e32 v173, 2, v173
	ds_bpermute_b32 v74, v172, v168
	ds_bpermute_b32 v75, v172, v169
	ds_bpermute_b32 v76, v172, v170
	ds_bpermute_b32 v77, v172, v171
	s_waitcnt lgkmcnt(3)
	v_add_f32_e32 v168, v168, v74
	s_waitcnt lgkmcnt(2)
	v_add_f32_e32 v169, v169, v75
	s_waitcnt lgkmcnt(1)
	v_add_f32_e32 v170, v170, v76
	s_waitcnt lgkmcnt(0)
	v_add_f32_e32 v171, v171, v77
	ds_bpermute_b32 v74, v173, v168
	ds_bpermute_b32 v75, v173, v169
	ds_bpermute_b32 v76, v173, v170
	ds_bpermute_b32 v77, v173, v171
	s_waitcnt lgkmcnt(3)
	v_add_f32_e32 v168, v168, v74
	s_waitcnt lgkmcnt(2)
	v_add_f32_e32 v169, v169, v75
	s_waitcnt lgkmcnt(1)
	v_add_f32_e32 v170, v170, v76
	s_waitcnt lgkmcnt(0)
	v_add_f32_e32 v171, v171, v77
	v_bfe_u32 v188, v177, 4, 2
	v_cmp_eq_u32_e32 vcc, 1, v188
	s_nop 1
	v_cndmask_b32_e32 v189, v168, v169, vcc
	v_cmp_eq_u32_e32 vcc, 2, v188
	s_nop 1
	v_cndmask_b32_e32 v189, v189, v170, vcc
	v_cmp_eq_u32_e32 vcc, 3, v188
	s_nop 1
	v_cndmask_b32_e32 v189, v189, v171, vcc
	v_mul_f32_e32 v189, 0x4b800000, v189
	v_trunc_f32_e32 v189, v189
	v_mul_f32_e32 v188, 0x2f800000, v189
	v_floor_f32_e32 v188, v188
	v_fmac_f32_e32 v189, 0xcf800000, v188
	v_cvt_u32_f32_e32 v172, v189
	v_cvt_u32_f32_e32 v173, v188
	s_lshl_b32 s7, s2, 3
	s_add_u32 s100, s46, s7
	s_addc_u32 s101, s47, 0
	v_lshlrev_b32_e32 v250, 3, v177
	global_atomic_add_x2 v250, v[172:173], s[100:101]
	s_waitcnt vmcnt(15)
; #define LAS __attribute__((address_space(3)))
; __device__ __forceinline__ float bf_lo(unsigned w) { return __uint_as_float(w << 16); }
; __device__ __forceinline__ float bf_hi(unsigned w) { return __uint_as_float(w & 0xffff0000u); }
; __device__ __forceinline__ unsigned cvt_pk_bf16(float lo, float hi) { unsigned r; asm volatile("v_cvt_pk_bf16_f32 %0, %1, %2" : "=v"(r) : "v"(lo), "v"(hi)); return r; }
;     __device__ __forceinline__ void operator()(const f32x4 (&acc)[2][2][4][2], const Unit& u, int wr, int wc, int fr, int fq) const {
;     ...
;             for (int m = 2 * mh; m < 2 * mh + 2; ++m) { const int rowb = u.pm * BM + ai * HALF + wr * 64 + m * 16;
; #pragma unroll
;                 for (int i = 0; i < 2; ++i) bs[m][i] = *(const u32x4*)(xb + (size_t)(rowb + rr + 8 * i) * DM + colw + cc * 8); }
; #pragma unroll
;             for (int m = 2 * mh; m < 2 * mh + 2; ++m) {
;                 const int rowb = u.pm * BM + ai * HALF + wr * 64 + m * 16; float q = 0.f;
; #pragma unroll
;                 for (int i = 0; i < 2; ++i) *(LAS u32x4*)(sl + (rr + 8 * i) * 144 + cc * 16) = bs[m][i];
; #pragma unroll
;                 for (int bj = 0; bj < 2; ++bj) {
;                     const u32x4 b4 = *(const LAS u32x4*)(sl + fr * 144 + bj * 64 + fq * 16);
;                     const f32x4 a0 = acc[ai][bj][m][0], a1 = acc[ai][bj][m][1];
;                     const float o0 = bf_lo(b4.x) + a0[0], o1 = bf_hi(b4.x) + a0[1], o2 = bf_lo(b4.y) + a0[2], o3 = bf_hi(b4.y) + a0[3];
;                     const float o4 = bf_lo(b4.z) + a1[0], o5 = bf_hi(b4.z) + a1[1], o6 = bf_lo(b4.w) + a1[2], o7 = bf_hi(b4.w) + a1[3];
;                     q += ((o0 * o0 + o1 * o1) + (o2 * o2 + o3 * o3)) + ((o4 * o4 + o5 * o5) + (o6 * o6 + o7 * o7));
;                     u32x4 w; w.x = cvt_pk_bf16(o0, o1); w.y = cvt_pk_bf16(o2, o3); w.z = cvt_pk_bf16(o4, o5); w.w = cvt_pk_bf16(o6, o7);
;                     *(LAS u32x4*)(sl + fr * 144 + bj * 64 + fq * 16) = w;
;                 }
; #pragma unroll
;                 for (int i = 0; i < 2; ++i) { const u32x4 qv = *(const LAS u32x4*)(sl + (rr + 8 * i) * 144 + cc * 16);
;                     *(u32x4*)(xb + (size_t)(rowb + rr + 8 * i) * DM + colw + cc * 8) = qv; }
	v_lshlrev_b32_e32 v172, 16, v238
	v_and_b32_e32 v173, 0xffff0000, v238
	v_pk_add_f32 v[62:63], v[62:63], v[172:173]
	v_lshlrev_b32_e32 v172, 16, v239
	v_and_b32_e32 v173, 0xffff0000, v239
	v_pk_add_f32 v[64:65], v[64:65], v[172:173]
	v_lshlrev_b32_e32 v172, 16, v240
	v_and_b32_e32 v173, 0xffff0000, v240
	v_pk_add_f32 v[58:59], v[58:59], v[172:173]
	v_lshlrev_b32_e32 v172, 16, v241
	v_and_b32_e32 v173, 0xffff0000, v241
	v_pk_add_f32 v[60:61], v[60:61], v[172:173]
	v_mul_f32_e32 v172, v63, v63
	v_mul_f32_e32 v173, v65, v65
	v_mul_f32_e32 v188, v59, v59
	v_mul_f32_e32 v189, v61, v61
	v_fmac_f32_e32 v172, v62, v62
	v_fmac_f32_e32 v173, v64, v64
	v_fmac_f32_e32 v188, v58, v58
	v_fmac_f32_e32 v189, v60, v60
	v_add_f32_e32 v172, v172, v173
	v_add_f32_e32 v188, v188, v189
	v_add_f32_e32 v172, v172, v188
	v_mov_b32_e32 v168, v172
	v_cvt_pk_bf16_f32 v62, v62, v63
	v_cvt_pk_bf16_f32 v63, v64, v65
	v_cvt_pk_bf16_f32 v64, v58, v59
	v_cvt_pk_bf16_f32 v65, v60, v61
	v_lshlrev_b32_e32 v172, 16, v242
	v_and_b32_e32 v173, 0xffff0000, v242
	v_pk_add_f32 v[54:55], v[54:55], v[172:173]
	v_lshlrev_b32_e32 v172, 16, v243
	v_and_b32_e32 v173, 0xffff0000, v243
	v_pk_add_f32 v[56:57], v[56:57], v[172:173]
	v_lshlrev_b32_e32 v172, 16, v244
	v_and_b32_e32 v173, 0xffff0000, v244
	v_pk_add_f32 v[50:51], v[50:51], v[172:173]
	v_lshlrev_b32_e32 v172, 16, v245
	v_and_b32_e32 v173, 0xffff0000, v245
	v_pk_add_f32 v[52:53], v[52:53], v[172:173]
	v_mul_f32_e32 v172, v55, v55
	v_mul_f32_e32 v173, v57, v57
	v_mul_f32_e32 v188, v51, v51
	v_mul_f32_e32 v189, v53, v53
	v_fmac_f32_e32 v172, v54, v54
	v_fmac_f32_e32 v173, v56, v56
	v_fmac_f32_e32 v188, v50, v50
	v_fmac_f32_e32 v189, v52, v52
	v_add_f32_e32 v172, v172, v173
	v_add_f32_e32 v188, v188, v189
	v_add_f32_e32 v172, v172, v188
	v_add_f32_e32 v168, v168, v172
	v_cvt_pk_bf16_f32 v54, v54, v55
	v_cvt_pk_bf16_f32 v55, v56, v57
	v_cvt_pk_bf16_f32 v56, v50, v51
	v_cvt_pk_bf16_f32 v57, v52, v53
	s_mov_b64 vcc, s[98:99]
	v_cndmask_b32_dpp v58, v62, v54, vcc quad_perm:[1,0,3,2] row_mask:0xf bank_mask:0xf
	v_cndmask_b32_dpp v59, v63, v55, vcc quad_perm:[1,0,3,2] row_mask:0xf bank_mask:0xf
	v_cndmask_b32_dpp v60, v64, v56, vcc quad_perm:[1,0,3,2] row_mask:0xf bank_mask:0xf
	v_cndmask_b32_dpp v61, v65, v57, vcc quad_perm:[1,0,3,2] row_mask:0xf bank_mask:0xf
	s_mov_b64 vcc, s[10:11]
	v_cndmask_b32_dpp v62, v54, v62, vcc quad_perm:[1,0,3,2] row_mask:0xf bank_mask:0xf
	v_cndmask_b32_dpp v63, v55, v63, vcc quad_perm:[1,0,3,2] row_mask:0xf bank_mask:0xf
	v_cndmask_b32_dpp v64, v56, v64, vcc quad_perm:[1,0,3,2] row_mask:0xf bank_mask:0xf
	v_cndmask_b32_dpp v65, v57, v65, vcc quad_perm:[1,0,3,2] row_mask:0xf bank_mask:0xf
	s_add_u32 s64, s62, 0x40000
	s_addc_u32 s65, s63, 0
	global_store_dwordx4 v251, v[62:65], s[64:65]
	global_store_dwordx4 v163, v[58:61], s[64:65]
	s_waitcnt vmcnt(15)
	v_lshlrev_b32_e32 v172, 16, v246
	v_and_b32_e32 v173, 0xffff0000, v246
	v_pk_add_f32 v[46:47], v[46:47], v[172:173]
	v_lshlrev_b32_e32 v172, 16, v247
	v_and_b32_e32 v173, 0xffff0000, v247
	v_pk_add_f32 v[48:49], v[48:49], v[172:173]
	v_lshlrev_b32_e32 v172, 16, v248
	v_and_b32_e32 v173, 0xffff0000, v248
	v_pk_add_f32 v[42:43], v[42:43], v[172:173]
	v_lshlrev_b32_e32 v172, 16, v249
	v_and_b32_e32 v173, 0xffff0000, v249
	v_pk_add_f32 v[44:45], v[44:45], v[172:173]
	v_mul_f32_e32 v172, v47, v47
	v_mul_f32_e32 v173, v49, v49
	v_mul_f32_e32 v188, v43, v43
	v_mul_f32_e32 v189, v45, v45
	v_fmac_f32_e32 v172, v46, v46
	v_fmac_f32_e32 v173, v48, v48
	v_fmac_f32_e32 v188, v42, v42
	v_fmac_f32_e32 v189, v44, v44
	v_add_f32_e32 v172, v172, v173
	v_add_f32_e32 v188, v188, v189
	v_add_f32_e32 v172, v172, v188
	v_mov_b32_e32 v169, v172
	v_cvt_pk_bf16_f32 v46, v46, v47
	v_cvt_pk_bf16_f32 v47, v48, v49
	v_cvt_pk_bf16_f32 v48, v42, v43
	v_cvt_pk_bf16_f32 v49, v44, v45
	v_lshlrev_b32_e32 v172, 16, v198
	v_and_b32_e32 v173, 0xffff0000, v198
	v_pk_add_f32 v[38:39], v[38:39], v[172:173]
	v_lshlrev_b32_e32 v172, 16, v199
	v_and_b32_e32 v173, 0xffff0000, v199
	v_pk_add_f32 v[40:41], v[40:41], v[172:173]
	v_lshlrev_b32_e32 v172, 16, v200
	v_and_b32_e32 v173, 0xffff0000, v200
	v_pk_add_f32 v[34:35], v[34:35], v[172:173]
	v_lshlrev_b32_e32 v172, 16, v201
	v_and_b32_e32 v173, 0xffff0000, v201
	v_pk_add_f32 v[36:37], v[36:37], v[172:173]
	v_mul_f32_e32 v172, v39, v39
	v_mul_f32_e32 v173, v41, v41
	v_mul_f32_e32 v188, v35, v35
	v_mul_f32_e32 v189, v37, v37
	v_fmac_f32_e32 v172, v38, v38
	v_fmac_f32_e32 v173, v40, v40
	v_fmac_f32_e32 v188, v34, v34
	v_fmac_f32_e32 v189, v36, v36
	v_add_f32_e32 v172, v172, v173
	v_add_f32_e32 v188, v188, v189
	v_add_f32_e32 v172, v172, v188
	v_add_f32_e32 v169, v169, v172
	v_cvt_pk_bf16_f32 v38, v38, v39
	v_cvt_pk_bf16_f32 v39, v40, v41
	v_cvt_pk_bf16_f32 v40, v34, v35
	v_cvt_pk_bf16_f32 v41, v36, v37
	s_mov_b64 vcc, s[98:99]
	v_cndmask_b32_dpp v42, v46, v38, vcc quad_perm:[1,0,3,2] row_mask:0xf bank_mask:0xf
	v_cndmask_b32_dpp v43, v47, v39, vcc quad_perm:[1,0,3,2] row_mask:0xf bank_mask:0xf
	v_cndmask_b32_dpp v44, v48, v40, vcc quad_perm:[1,0,3,2] row_mask:0xf bank_mask:0xf
	v_cndmask_b32_dpp v45, v49, v41, vcc quad_perm:[1,0,3,2] row_mask:0xf bank_mask:0xf
	s_mov_b64 vcc, s[10:11]
	v_cndmask_b32_dpp v46, v38, v46, vcc quad_perm:[1,0,3,2] row_mask:0xf bank_mask:0xf
	v_cndmask_b32_dpp v47, v39, v47, vcc quad_perm:[1,0,3,2] row_mask:0xf bank_mask:0xf
	v_cndmask_b32_dpp v48, v40, v48, vcc quad_perm:[1,0,3,2] row_mask:0xf bank_mask:0xf
	v_cndmask_b32_dpp v49, v41, v49, vcc quad_perm:[1,0,3,2] row_mask:0xf bank_mask:0xf
	s_add_u32 s64, s62, 0x48000
	s_addc_u32 s65, s63, 0
	global_store_dwordx4 v251, v[46:49], s[64:65]
	global_store_dwordx4 v163, v[42:45], s[64:65]
	s_waitcnt vmcnt(15)
; #define LAS __attribute__((address_space(3)))
; __device__ __forceinline__ float bf_lo(unsigned w) { return __uint_as_float(w << 16); }
; __device__ __forceinline__ float bf_hi(unsigned w) { return __uint_as_float(w & 0xffff0000u); }
; __device__ __forceinline__ unsigned cvt_pk_bf16(float lo, float hi) { unsigned r; asm volatile("v_cvt_pk_bf16_f32 %0, %1, %2" : "=v"(r) : "v"(lo), "v"(hi)); return r; }
;     __device__ __forceinline__ void operator()(const f32x4 (&acc)[2][2][4][2], const Unit& u, int wr, int wc, int fr, int fq) const {
;     ...
;             for (int m = 2 * mh; m < 2 * mh + 2; ++m) { const int rowb = u.pm * BM + ai * HALF + wr * 64 + m * 16;
; #pragma unroll
;                 for (int i = 0; i < 2; ++i) bs[m][i] = *(const u32x4*)(xb + (size_t)(rowb + rr + 8 * i) * DM + colw + cc * 8); }
; #pragma unroll
;             for (int m = 2 * mh; m < 2 * mh + 2; ++m) {
;                 const int rowb = u.pm * BM + ai * HALF + wr * 64 + m * 16; float q = 0.f;
; #pragma unroll
;                 for (int i = 0; i < 2; ++i) *(LAS u32x4*)(sl + (rr + 8 * i) * 144 + cc * 16) = bs[m][i];
; #pragma unroll
;                 for (int bj = 0; bj < 2; ++bj) {
;                     const u32x4 b4 = *(const LAS u32x4*)(sl + fr * 144 + bj * 64 + fq * 16);
;                     const f32x4 a0 = acc[ai][bj][m][0], a1 = acc[ai][bj][m][1];
;                     const float o0 = bf_lo(b4.x) + a0[0], o1 = bf_hi(b4.x) + a0[1], o2 = bf_lo(b4.y) + a0[2], o3 = bf_hi(b4.y) + a0[3];
;                     const float o4 = bf_lo(b4.z) + a1[0], o5 = bf_hi(b4.z) + a1[1], o6 = bf_lo(b4.w) + a1[2], o7 = bf_hi(b4.w) + a1[3];
;                     q += ((o0 * o0 + o1 * o1) + (o2 * o2 + o3 * o3)) + ((o4 * o4 + o5 * o5) + (o6 * o6 + o7 * o7));
;                     u32x4 w; w.x = cvt_pk_bf16(o0, o1); w.y = cvt_pk_bf16(o2, o3); w.z = cvt_pk_bf16(o4, o5); w.w = cvt_pk_bf16(o6, o7);
;                     *(LAS u32x4*)(sl + fr * 144 + bj * 64 + fq * 16) = w;
;                 }
; #pragma unroll
;                 for (int i = 0; i < 2; ++i) { const u32x4 qv = *(const LAS u32x4*)(sl + (rr + 8 * i) * 144 + cc * 16);
;                     *(u32x4*)(xb + (size_t)(rowb + rr + 8 * i) * DM + colw + cc * 8) = qv; }
	v_lshlrev_b32_e32 v172, 16, v202
	v_and_b32_e32 v173, 0xffff0000, v202
	v_pk_add_f32 v[30:31], v[30:31], v[172:173]
	v_lshlrev_b32_e32 v172, 16, v203
	v_and_b32_e32 v173, 0xffff0000, v203
	v_pk_add_f32 v[32:33], v[32:33], v[172:173]
	v_lshlrev_b32_e32 v172, 16, v204
	v_and_b32_e32 v173, 0xffff0000, v204
	v_pk_add_f32 v[26:27], v[26:27], v[172:173]
	v_lshlrev_b32_e32 v172, 16, v205
	v_and_b32_e32 v173, 0xffff0000, v205
	v_pk_add_f32 v[28:29], v[28:29], v[172:173]
	v_mul_f32_e32 v172, v31, v31
	v_mul_f32_e32 v173, v33, v33
	v_mul_f32_e32 v188, v27, v27
	v_mul_f32_e32 v189, v29, v29
	v_fmac_f32_e32 v172, v30, v30
	v_fmac_f32_e32 v173, v32, v32
	v_fmac_f32_e32 v188, v26, v26
	v_fmac_f32_e32 v189, v28, v28
	v_add_f32_e32 v172, v172, v173
	v_add_f32_e32 v188, v188, v189
	v_add_f32_e32 v172, v172, v188
	v_mov_b32_e32 v170, v172
	v_cvt_pk_bf16_f32 v30, v30, v31
	v_cvt_pk_bf16_f32 v31, v32, v33
	v_cvt_pk_bf16_f32 v32, v26, v27
	v_cvt_pk_bf16_f32 v33, v28, v29
	v_lshlrev_b32_e32 v172, 16, v130
	v_and_b32_e32 v173, 0xffff0000, v130
	v_pk_add_f32 v[22:23], v[22:23], v[172:173]
	v_lshlrev_b32_e32 v172, 16, v131
	v_and_b32_e32 v173, 0xffff0000, v131
	v_pk_add_f32 v[24:25], v[24:25], v[172:173]
	v_lshlrev_b32_e32 v172, 16, v132
	v_and_b32_e32 v173, 0xffff0000, v132
	v_pk_add_f32 v[18:19], v[18:19], v[172:173]
	v_lshlrev_b32_e32 v172, 16, v133
	v_and_b32_e32 v173, 0xffff0000, v133
	v_pk_add_f32 v[20:21], v[20:21], v[172:173]
	v_mul_f32_e32 v172, v23, v23
	v_mul_f32_e32 v173, v25, v25
	v_mul_f32_e32 v188, v19, v19
	v_mul_f32_e32 v189, v21, v21
	v_fmac_f32_e32 v172, v22, v22
	v_fmac_f32_e32 v173, v24, v24
	v_fmac_f32_e32 v188, v18, v18
	v_fmac_f32_e32 v189, v20, v20
	v_add_f32_e32 v172, v172, v173
	v_add_f32_e32 v188, v188, v189
	v_add_f32_e32 v172, v172, v188
	v_add_f32_e32 v170, v170, v172
	v_cvt_pk_bf16_f32 v22, v22, v23
	v_cvt_pk_bf16_f32 v23, v24, v25
	v_cvt_pk_bf16_f32 v24, v18, v19
	v_cvt_pk_bf16_f32 v25, v20, v21
	s_mov_b64 vcc, s[98:99]
	v_cndmask_b32_dpp v26, v30, v22, vcc quad_perm:[1,0,3,2] row_mask:0xf bank_mask:0xf
	v_cndmask_b32_dpp v27, v31, v23, vcc quad_perm:[1,0,3,2] row_mask:0xf bank_mask:0xf
	v_cndmask_b32_dpp v28, v32, v24, vcc quad_perm:[1,0,3,2] row_mask:0xf bank_mask:0xf
	v_cndmask_b32_dpp v29, v33, v25, vcc quad_perm:[1,0,3,2] row_mask:0xf bank_mask:0xf
	s_mov_b64 vcc, s[10:11]
	v_cndmask_b32_dpp v30, v22, v30, vcc quad_perm:[1,0,3,2] row_mask:0xf bank_mask:0xf
	v_cndmask_b32_dpp v31, v23, v31, vcc quad_perm:[1,0,3,2] row_mask:0xf bank_mask:0xf
	v_cndmask_b32_dpp v32, v24, v32, vcc quad_perm:[1,0,3,2] row_mask:0xf bank_mask:0xf
	v_cndmask_b32_dpp v33, v25, v33, vcc quad_perm:[1,0,3,2] row_mask:0xf bank_mask:0xf
	s_add_u32 s64, s62, 0x50000
	s_addc_u32 s65, s63, 0
	global_store_dwordx4 v251, v[30:33], s[64:65]
	global_store_dwordx4 v163, v[26:29], s[64:65]
	s_waitcnt vmcnt(15)
; #define LAS __attribute__((address_space(3)))
;     __device__ __forceinline__ void operator()(const f32x4 (&acc)[2][2][4][2], const Unit& u, int wr, int wc, int fr, int fq) const {
;     ...
;             for (int m = 2 * mh; m < 2 * mh + 2; ++m) { const int rowb = u.pm * BM + ai * HALF + wr * 64 + m * 16;
; #pragma unroll
;                 for (int i = 0; i < 2; ++i) bs[m][i] = *(const u32x4*)(xb + (size_t)(rowb + rr + 8 * i) * DM + colw + cc * 8); }
; #pragma unroll
;             for (int m = 2 * mh; m < 2 * mh + 2; ++m) {
;                 const int rowb = u.pm * BM + ai * HALF + wr * 64 + m * 16; float q = 0.f;
; #pragma unroll
;                 for (int i = 0; i < 2; ++i) *(LAS u32x4*)(sl + (rr + 8 * i) * 144 + cc * 16) = bs[m][i];
; #pragma unroll
;                 for (int bj = 0; bj < 2; ++bj) {
;                     const u32x4 b4 = *(const LAS u32x4*)(sl + fr * 144 + bj * 64 + fq * 16);
;                     const f32x4 a0 = acc[ai][bj][m][0], a1 = acc[ai][bj][m][1];
;                     const float o0 = bf_lo(b4.x) + a0[0], o1 = bf_hi(b4.x) + a0[1], o2 = bf_lo(b4.y) + a0[2], o3 = bf_hi(b4.y) + a0[3];
;                     const float o4 = bf_lo(b4.z) + a1[0], o5 = bf_hi(b4.z) + a1[1], o6 = bf_lo(b4.w) + a1[2], o7 = bf_hi(b4.w) + a1[3];
;                     q += ((o0 * o0 + o1 * o1) + (o2 * o2 + o3 * o3)) + ((o4 * o4 + o5 * o5) + (o6 * o6 + o7 * o7));
;                     u32x4 w; w.x = cvt_pk_bf16(o0, o1); w.y = cvt_pk_bf16(o2, o3); w.z = cvt_pk_bf16(o4, o5); w.w = cvt_pk_bf16(o6, o7);
;                     *(LAS u32x4*)(sl + fr * 144 + bj * 64 + fq * 16) = w;
;                 }
; #pragma unroll
;                 for (int i = 0; i < 2; ++i) { const u32x4 qv = *(const LAS u32x4*)(sl + (rr + 8 * i) * 144 + cc * 16);
;                     *(u32x4*)(xb + (size_t)(rowb + rr + 8 * i) * DM + colw + cc * 8) = qv; }
;                 q += __shfl_xor(q, 16); q += __shfl_xor(q, 32); qs[m] = q;
;             }
;             asm volatile("" ::: "memory");
;             }
;             { const float mine = fq == 0 ? qs[0] : (fq == 1 ? qs[1] : (fq == 2 ? qs[2] : qs[3]));
;               __hip_atomic_fetch_add(ssq + (u.pm * BM + ai * HALF + wr * 64 + 16 * fq + fr), (u64)(mine * 16777216.0f), __ATOMIC_RELAXED, __HIP_MEMORY_SCOPE_AGENT); }
;             asm volatile("" ::: "memory");
;         }
	v_lshlrev_b32_e32 v172, 16, v134
	v_and_b32_e32 v173, 0xffff0000, v134
	v_pk_add_f32 v[14:15], v[14:15], v[172:173]
	v_lshlrev_b32_e32 v172, 16, v135
	v_and_b32_e32 v173, 0xffff0000, v135
	v_pk_add_f32 v[16:17], v[16:17], v[172:173]
	v_lshlrev_b32_e32 v172, 16, v136
	v_and_b32_e32 v173, 0xffff0000, v136
	v_pk_add_f32 v[10:11], v[10:11], v[172:173]
	v_lshlrev_b32_e32 v172, 16, v137
	v_and_b32_e32 v173, 0xffff0000, v137
	v_pk_add_f32 v[12:13], v[12:13], v[172:173]
	v_mul_f32_e32 v172, v15, v15
	v_mul_f32_e32 v173, v17, v17
	v_mul_f32_e32 v188, v11, v11
	v_mul_f32_e32 v189, v13, v13
	v_fmac_f32_e32 v172, v14, v14
	v_fmac_f32_e32 v173, v16, v16
	v_fmac_f32_e32 v188, v10, v10
	v_fmac_f32_e32 v189, v12, v12
	v_add_f32_e32 v172, v172, v173
	v_add_f32_e32 v188, v188, v189
	v_add_f32_e32 v172, v172, v188
	v_mov_b32_e32 v171, v172
	v_cvt_pk_bf16_f32 v14, v14, v15
	v_cvt_pk_bf16_f32 v15, v16, v17
	v_cvt_pk_bf16_f32 v16, v10, v11
	v_cvt_pk_bf16_f32 v17, v12, v13
	v_lshlrev_b32_e32 v172, 16, v164
	v_and_b32_e32 v173, 0xffff0000, v164
	v_pk_add_f32 v[6:7], v[6:7], v[172:173]
	v_lshlrev_b32_e32 v172, 16, v165
	v_and_b32_e32 v173, 0xffff0000, v165
	v_pk_add_f32 v[8:9], v[8:9], v[172:173]
	v_lshlrev_b32_e32 v172, 16, v166
	v_and_b32_e32 v173, 0xffff0000, v166
	v_pk_add_f32 v[2:3], v[2:3], v[172:173]
	v_lshlrev_b32_e32 v172, 16, v167
	v_and_b32_e32 v173, 0xffff0000, v167
	v_pk_add_f32 v[4:5], v[4:5], v[172:173]
	v_mul_f32_e32 v172, v7, v7
	v_mul_f32_e32 v173, v9, v9
	v_mul_f32_e32 v188, v3, v3
	v_mul_f32_e32 v189, v5, v5
	v_fmac_f32_e32 v172, v6, v6
	v_fmac_f32_e32 v173, v8, v8
	v_fmac_f32_e32 v188, v2, v2
	v_fmac_f32_e32 v189, v4, v4
	v_add_f32_e32 v172, v172, v173
	v_add_f32_e32 v188, v188, v189
	v_add_f32_e32 v172, v172, v188
	v_add_f32_e32 v171, v171, v172
	v_cvt_pk_bf16_f32 v6, v6, v7
	v_cvt_pk_bf16_f32 v7, v8, v9
	v_cvt_pk_bf16_f32 v8, v2, v3
	v_cvt_pk_bf16_f32 v9, v4, v5
	s_mov_b64 vcc, s[98:99]
	v_cndmask_b32_dpp v10, v14, v6, vcc quad_perm:[1,0,3,2] row_mask:0xf bank_mask:0xf
	v_cndmask_b32_dpp v11, v15, v7, vcc quad_perm:[1,0,3,2] row_mask:0xf bank_mask:0xf
	v_cndmask_b32_dpp v12, v16, v8, vcc quad_perm:[1,0,3,2] row_mask:0xf bank_mask:0xf
	v_cndmask_b32_dpp v13, v17, v9, vcc quad_perm:[1,0,3,2] row_mask:0xf bank_mask:0xf
	s_mov_b64 vcc, s[10:11]
	v_cndmask_b32_dpp v14, v6, v14, vcc quad_perm:[1,0,3,2] row_mask:0xf bank_mask:0xf
	v_cndmask_b32_dpp v15, v7, v15, vcc quad_perm:[1,0,3,2] row_mask:0xf bank_mask:0xf
	v_cndmask_b32_dpp v16, v8, v16, vcc quad_perm:[1,0,3,2] row_mask:0xf bank_mask:0xf
	v_cndmask_b32_dpp v17, v9, v17, vcc quad_perm:[1,0,3,2] row_mask:0xf bank_mask:0xf
	s_add_u32 s64, s62, 0x58000
	s_addc_u32 s65, s63, 0
	global_store_dwordx4 v251, v[14:17], s[64:65]
	global_store_dwordx4 v163, v[10:13], s[64:65]
	v_xor_b32_e32 v172, 16, v177
	v_lshlrev_b32_e32 v172, 2, v172
	v_xor_b32_e32 v173, 32, v177
	v_lshlrev_b32_e32 v173, 2, v173
	ds_bpermute_b32 v10, v172, v168
	ds_bpermute_b32 v11, v172, v169
	ds_bpermute_b32 v12, v172, v170
	ds_bpermute_b32 v13, v172, v171
	s_waitcnt lgkmcnt(3)
	v_add_f32_e32 v168, v168, v10
	s_waitcnt lgkmcnt(2)
	v_add_f32_e32 v169, v169, v11
	s_waitcnt lgkmcnt(1)
	v_add_f32_e32 v170, v170, v12
	s_waitcnt lgkmcnt(0)
	v_add_f32_e32 v171, v171, v13
	ds_bpermute_b32 v10, v173, v168
	ds_bpermute_b32 v11, v173, v169
	ds_bpermute_b32 v12, v173, v170
	ds_bpermute_b32 v13, v173, v171
	s_waitcnt lgkmcnt(3)
	v_add_f32_e32 v168, v168, v10
	s_waitcnt lgkmcnt(2)
	v_add_f32_e32 v169, v169, v11
	s_waitcnt lgkmcnt(1)
	v_add_f32_e32 v170, v170, v12
	s_waitcnt lgkmcnt(0)
	v_add_f32_e32 v171, v171, v13
	v_bfe_u32 v188, v177, 4, 2
	v_cmp_eq_u32_e32 vcc, 1, v188
	s_nop 1
	v_cndmask_b32_e32 v189, v168, v169, vcc
	v_cmp_eq_u32_e32 vcc, 2, v188
	s_nop 1
	v_cndmask_b32_e32 v189, v189, v170, vcc
	v_cmp_eq_u32_e32 vcc, 3, v188
	s_nop 1
	v_cndmask_b32_e32 v189, v189, v171, vcc
	v_mul_f32_e32 v189, 0x4b800000, v189
	v_trunc_f32_e32 v189, v189
	v_mul_f32_e32 v188, 0x2f800000, v189
	v_floor_f32_e32 v188, v188
	v_fmac_f32_e32 v189, 0xcf800000, v188
	v_cvt_u32_f32_e32 v172, v189
	v_cvt_u32_f32_e32 v173, v188
	s_andn2_b64 vcc, exec, s[40:41]
	s_mov_b64 s[26:27], -1
	global_atomic_add_x2 v250, v[172:173], s[100:101] offset:1024
	s_cbranch_vccnz .LBB0_418
	s_andn2_b64 vcc, exec, s[42:43]
	s_cbranch_vccnz .LBB0_417
	s_barrier
	s_branch .LBB0_417

; #define LAS __attribute__((address_space(3)))
; __device__ __forceinline__ float bf_lo(unsigned w) { return __uint_as_float(w << 16); }
;     __device__ __forceinline__ void operator()(const f32x4 (&acc)[2][2][4][2], const Unit& u, int wr, int wc, int fr, int fq) const {
;         const int ln = fr + 16 * fq, rr = ln >> 3, cc = ln & 7; const int colw = u.pn * BM + 64 * wc;
;         LAS unsigned char* sl = stg + (wr * 4 + wc) * EPI_STG_SLICE;
; #pragma unroll
;         for (int ai = 0; ai < 2; ++ai) {
;             float qs[4];
; #pragma unroll
;             for (int mh = 0; mh < 2; ++mh) {
;             u32x4 bs[4][2];
; #pragma unroll
;             for (int m = 2 * mh; m < 2 * mh + 2; ++m) { const int rowb = u.pm * BM + ai * HALF + wr * 64 + m * 16;
; #pragma unroll
;                 for (int i = 0; i < 2; ++i) bs[m][i] = *(const u32x4*)(xb + (size_t)(rowb + rr + 8 * i) * DM + colw + cc * 8); }
; #pragma unroll
;             for (int m = 2 * mh; m < 2 * mh + 2; ++m) {
;                 const int rowb = u.pm * BM + ai * HALF + wr * 64 + m * 16; float q = 0.f;
; #pragma unroll
;                 for (int i = 0; i < 2; ++i) *(LAS u32x4*)(sl + (rr + 8 * i) * 144 + cc * 16) = bs[m][i];
; #pragma unroll
;                 for (int bj = 0; bj < 2; ++bj) {
;                     const u32x4 b4 = *(const LAS u32x4*)(sl + fr * 144 + bj * 64 + fq * 16);
;                     const f32x4 a0 = acc[ai][bj][m][0], a1 = acc[ai][bj][m][1];
;                     const float o0 = bf_lo(b4.x) + a0[0], o1 = bf_hi(b4.x) + a0[1], o2 = bf_lo(b4.y) + a0[2], o3 = bf_hi(b4.y) + a0[3];
;                     const float o4 = bf_lo(b4.z) + a1[0], o5 = bf_hi(b4.z) + a1[1], o6 = bf_lo(b4.w) + a1[2], o7 = bf_hi(b4.w) + a1[3];
;                     q += ((o0 * o0 + o1 * o1) + (o2 * o2 + o3 * o3)) + ((o4 * o4 + o5 * o5) + (o6 * o6 + o7 * o7));
;                     u32x4 w; w.x = cvt_pk_bf16(o0, o1); w.y = cvt_pk_bf16(o2, o3); w.z = cvt_pk_bf16(o4, o5); w.w = cvt_pk_bf16(o6, o7);
;                     *(LAS u32x4*)(sl + fr * 144 + bj * 64 + fq * 16) = w;
;                 }
; #pragma unroll
;                 for (int i = 0; i < 2; ++i) { const u32x4 qv = *(const LAS u32x4*)(sl + (rr + 8 * i) * 144 + cc * 16);
;                     *(u32x4*)(xb + (size_t)(rowb + rr + 8 * i) * DM + colw + cc * 8) = qv; }
.LBB0_591:
	s_lshl_b32 s2, s2, 8
	s_or_b32 s4, s2, s82
	s_lshl_b32 s2, s3, 8
	s_add_i32 s2, s2, s79
	s_lshl_b32 s7, s2, 11
	s_lshl_b32 s32, s4, 1
	s_add_u32 s7, s7, s32
	s_add_u32 s62, s40, s7
	s_addc_u32 s63, s41, 0
	v_and_b32_e32 v172, 15, v177
	v_bfe_u32 v173, v177, 4, 2
	v_lshlrev_b32_e32 v250, 11, v172
	v_lshl_add_u32 v250, v173, 4, v250
	v_and_b32_e32 v188, 1, v177
	v_and_b32_e32 v189, 14, v177
	v_cmp_eq_u32_e64 s[10:11], 0, v188
	v_cmp_ne_u32_e64 s[98:99], 0, v188
	v_lshlrev_b32_e32 v251, 11, v189
	v_lshl_add_u32 v251, v188, 6, v251
	v_lshl_add_u32 v251, v173, 4, v251
	v_add_u32_e32 v163, 0x800, v251
	s_mov_b32 s64, s62
	s_mov_b32 s65, s63
	global_load_dwordx4 v[206:209], v250, s[64:65]
	global_load_dwordx4 v[210:213], v250, s[64:65] offset:64
	s_add_u32 s64, s62, 0x8000
	s_addc_u32 s65, s63, 0
	global_load_dwordx4 v[214:217], v250, s[64:65]
	global_load_dwordx4 v[218:221], v250, s[64:65] offset:64
	s_add_u32 s64, s62, 0x10000
	s_addc_u32 s65, s63, 0
	global_load_dwordx4 v[222:225], v250, s[64:65]
	global_load_dwordx4 v[226:229], v250, s[64:65] offset:64
	s_add_u32 s64, s62, 0x18000
	s_addc_u32 s65, s63, 0
	global_load_dwordx4 v[230:233], v250, s[64:65]
	global_load_dwordx4 v[234:237], v250, s[64:65] offset:64
	s_add_u32 s64, s62, 0x40000
	s_addc_u32 s65, s63, 0
	global_load_dwordx4 v[238:241], v250, s[64:65]
	global_load_dwordx4 v[242:245], v250, s[64:65] offset:64
	s_add_u32 s64, s62, 0x48000
	s_addc_u32 s65, s63, 0
	global_load_dwordx4 v[246:249], v250, s[64:65]
	global_load_dwordx4 v[198:201], v250, s[64:65] offset:64
	s_add_u32 s64, s62, 0x50000
	s_addc_u32 s65, s63, 0
	global_load_dwordx4 v[202:205], v250, s[64:65]
	global_load_dwordx4 v[130:133], v250, s[64:65] offset:64
	s_add_u32 s64, s62, 0x58000
	s_addc_u32 s65, s63, 0
	global_load_dwordx4 v[134:137], v250, s[64:65]
	global_load_dwordx4 v[164:167], v250, s[64:65] offset:64
	s_waitcnt vmcnt(14)
	v_lshlrev_b32_e32 v172, 16, v206
	v_and_b32_e32 v173, 0xffff0000, v206
	v_pk_add_f32 v[126:127], v[126:127], v[172:173]
	v_lshlrev_b32_e32 v172, 16, v207
	v_and_b32_e32 v173, 0xffff0000, v207
	v_pk_add_f32 v[128:129], v[128:129], v[172:173]
	v_lshlrev_b32_e32 v172, 16, v208
	v_and_b32_e32 v173, 0xffff0000, v208
	v_pk_add_f32 v[122:123], v[122:123], v[172:173]
	v_lshlrev_b32_e32 v172, 16, v209
	v_and_b32_e32 v173, 0xffff0000, v209
	v_pk_add_f32 v[124:125], v[124:125], v[172:173]
	v_mul_f32_e32 v172, v127, v127
	v_mul_f32_e32 v173, v129, v129
	v_mul_f32_e32 v188, v123, v123
	v_mul_f32_e32 v189, v125, v125
	v_fmac_f32_e32 v172, v126, v126
	v_fmac_f32_e32 v173, v128, v128
	v_fmac_f32_e32 v188, v122, v122
	v_fmac_f32_e32 v189, v124, v124
	v_add_f32_e32 v172, v172, v173
	v_add_f32_e32 v188, v188, v189
	v_add_f32_e32 v172, v172, v188
	v_mov_b32_e32 v168, v172
	v_cvt_pk_bf16_f32 v126, v126, v127
	v_cvt_pk_bf16_f32 v127, v128, v129
	v_cvt_pk_bf16_f32 v128, v122, v123
	v_cvt_pk_bf16_f32 v129, v124, v125
	v_lshlrev_b32_e32 v172, 16, v210
	v_and_b32_e32 v173, 0xffff0000, v210
	v_pk_add_f32 v[118:119], v[118:119], v[172:173]
	v_lshlrev_b32_e32 v172, 16, v211
	v_and_b32_e32 v173, 0xffff0000, v211
	v_pk_add_f32 v[120:121], v[120:121], v[172:173]
	v_lshlrev_b32_e32 v172, 16, v212
	v_and_b32_e32 v173, 0xffff0000, v212
	v_pk_add_f32 v[114:115], v[114:115], v[172:173]
	v_lshlrev_b32_e32 v172, 16, v213
	v_and_b32_e32 v173, 0xffff0000, v213
	v_pk_add_f32 v[116:117], v[116:117], v[172:173]
	v_mul_f32_e32 v172, v119, v119
	v_mul_f32_e32 v173, v121, v121
	v_mul_f32_e32 v188, v115, v115
	v_mul_f32_e32 v189, v117, v117
	v_fmac_f32_e32 v172, v118, v118
	v_fmac_f32_e32 v173, v120, v120
	v_fmac_f32_e32 v188, v114, v114
	v_fmac_f32_e32 v189, v116, v116
	v_add_f32_e32 v172, v172, v173
	v_add_f32_e32 v188, v188, v189
	v_add_f32_e32 v172, v172, v188
	v_add_f32_e32 v168, v168, v172
	v_cvt_pk_bf16_f32 v118, v118, v119
	v_cvt_pk_bf16_f32 v119, v120, v121
	v_cvt_pk_bf16_f32 v120, v114, v115
	v_cvt_pk_bf16_f32 v121, v116, v117
	s_mov_b64 vcc, s[98:99]
	v_cndmask_b32_dpp v122, v126, v118, vcc quad_perm:[1,0,3,2] row_mask:0xf bank_mask:0xf
	v_cndmask_b32_dpp v123, v127, v119, vcc quad_perm:[1,0,3,2] row_mask:0xf bank_mask:0xf
	v_cndmask_b32_dpp v124, v128, v120, vcc quad_perm:[1,0,3,2] row_mask:0xf bank_mask:0xf
	v_cndmask_b32_dpp v125, v129, v121, vcc quad_perm:[1,0,3,2] row_mask:0xf bank_mask:0xf
	s_mov_b64 vcc, s[10:11]
	v_cndmask_b32_dpp v126, v118, v126, vcc quad_perm:[1,0,3,2] row_mask:0xf bank_mask:0xf
	v_cndmask_b32_dpp v127, v119, v127, vcc quad_perm:[1,0,3,2] row_mask:0xf bank_mask:0xf
	v_cndmask_b32_dpp v128, v120, v128, vcc quad_perm:[1,0,3,2] row_mask:0xf bank_mask:0xf
	v_cndmask_b32_dpp v129, v121, v129, vcc quad_perm:[1,0,3,2] row_mask:0xf bank_mask:0xf
	s_mov_b32 s64, s62
	s_mov_b32 s65, s63
	global_store_dwordx4 v251, v[126:129], s[64:65]
	global_store_dwordx4 v163, v[122:125], s[64:65]
	s_waitcnt vmcnt(14)
; #define LAS __attribute__((address_space(3)))
; __device__ __forceinline__ float bf_lo(unsigned w) { return __uint_as_float(w << 16); }
; __device__ __forceinline__ float bf_hi(unsigned w) { return __uint_as_float(w & 0xffff0000u); }
; __device__ __forceinline__ unsigned cvt_pk_bf16(float lo, float hi) { unsigned r; asm volatile("v_cvt_pk_bf16_f32 %0, %1, %2" : "=v"(r) : "v"(lo), "v"(hi)); return r; }
;     __device__ __forceinline__ void operator()(const f32x4 (&acc)[2][2][4][2], const Unit& u, int wr, int wc, int fr, int fq) const {
;     ...
;             for (int m = 2 * mh; m < 2 * mh + 2; ++m) { const int rowb = u.pm * BM + ai * HALF + wr * 64 + m * 16;
; #pragma unroll
;                 for (int i = 0; i < 2; ++i) bs[m][i] = *(const u32x4*)(xb + (size_t)(rowb + rr + 8 * i) * DM + colw + cc * 8); }
; #pragma unroll
;             for (int m = 2 * mh; m < 2 * mh + 2; ++m) {
;                 const int rowb = u.pm * BM + ai * HALF + wr * 64 + m * 16; float q = 0.f;
; #pragma unroll
;                 for (int i = 0; i < 2; ++i) *(LAS u32x4*)(sl + (rr + 8 * i) * 144 + cc * 16) = bs[m][i];
; #pragma unroll
;                 for (int bj = 0; bj < 2; ++bj) {
;                     const u32x4 b4 = *(const LAS u32x4*)(sl + fr * 144 + bj * 64 + fq * 16);
;                     const f32x4 a0 = acc[ai][bj][m][0], a1 = acc[ai][bj][m][1];
;                     const float o0 = bf_lo(b4.x) + a0[0], o1 = bf_hi(b4.x) + a0[1], o2 = bf_lo(b4.y) + a0[2], o3 = bf_hi(b4.y) + a0[3];
;                     const float o4 = bf_lo(b4.z) + a1[0], o5 = bf_hi(b4.z) + a1[1], o6 = bf_lo(b4.w) + a1[2], o7 = bf_hi(b4.w) + a1[3];
;                     q += ((o0 * o0 + o1 * o1) + (o2 * o2 + o3 * o3)) + ((o4 * o4 + o5 * o5) + (o6 * o6 + o7 * o7));
;                     u32x4 w; w.x = cvt_pk_bf16(o0, o1); w.y = cvt_pk_bf16(o2, o3); w.z = cvt_pk_bf16(o4, o5); w.w = cvt_pk_bf16(o6, o7);
;                     *(LAS u32x4*)(sl + fr * 144 + bj * 64 + fq * 16) = w;
;                 }
; #pragma unroll
;                 for (int i = 0; i < 2; ++i) { const u32x4 qv = *(const LAS u32x4*)(sl + (rr + 8 * i) * 144 + cc * 16);
;                     *(u32x4*)(xb + (size_t)(rowb + rr + 8 * i) * DM + colw + cc * 8) = qv; }
	v_lshlrev_b32_e32 v172, 16, v214
	v_and_b32_e32 v173, 0xffff0000, v214
	v_pk_add_f32 v[110:111], v[110:111], v[172:173]
	v_lshlrev_b32_e32 v172, 16, v215
	v_and_b32_e32 v173, 0xffff0000, v215
	v_pk_add_f32 v[112:113], v[112:113], v[172:173]
	v_lshlrev_b32_e32 v172, 16, v216
	v_and_b32_e32 v173, 0xffff0000, v216
	v_pk_add_f32 v[106:107], v[106:107], v[172:173]
	v_lshlrev_b32_e32 v172, 16, v217
	v_and_b32_e32 v173, 0xffff0000, v217
	v_pk_add_f32 v[108:109], v[108:109], v[172:173]
	v_mul_f32_e32 v172, v111, v111
	v_mul_f32_e32 v173, v113, v113
	v_mul_f32_e32 v188, v107, v107
	v_mul_f32_e32 v189, v109, v109
	v_fmac_f32_e32 v172, v110, v110
	v_fmac_f32_e32 v173, v112, v112
	v_fmac_f32_e32 v188, v106, v106
	v_fmac_f32_e32 v189, v108, v108
	v_add_f32_e32 v172, v172, v173
	v_add_f32_e32 v188, v188, v189
	v_add_f32_e32 v172, v172, v188
	v_mov_b32_e32 v169, v172
	v_cvt_pk_bf16_f32 v110, v110, v111
	v_cvt_pk_bf16_f32 v111, v112, v113
	v_cvt_pk_bf16_f32 v112, v106, v107
	v_cvt_pk_bf16_f32 v113, v108, v109
	v_lshlrev_b32_e32 v172, 16, v218
	v_and_b32_e32 v173, 0xffff0000, v218
	v_pk_add_f32 v[102:103], v[102:103], v[172:173]
	v_lshlrev_b32_e32 v172, 16, v219
	v_and_b32_e32 v173, 0xffff0000, v219
	v_pk_add_f32 v[104:105], v[104:105], v[172:173]
	v_lshlrev_b32_e32 v172, 16, v220
	v_and_b32_e32 v173, 0xffff0000, v220
	v_pk_add_f32 v[98:99], v[98:99], v[172:173]
	v_lshlrev_b32_e32 v172, 16, v221
	v_and_b32_e32 v173, 0xffff0000, v221
	v_pk_add_f32 v[100:101], v[100:101], v[172:173]
	v_mul_f32_e32 v172, v103, v103
	v_mul_f32_e32 v173, v105, v105
	v_mul_f32_e32 v188, v99, v99
	v_mul_f32_e32 v189, v101, v101
	v_fmac_f32_e32 v172, v102, v102
	v_fmac_f32_e32 v173, v104, v104
	v_fmac_f32_e32 v188, v98, v98
	v_fmac_f32_e32 v189, v100, v100
	v_add_f32_e32 v172, v172, v173
	v_add_f32_e32 v188, v188, v189
	v_add_f32_e32 v172, v172, v188
	v_add_f32_e32 v169, v169, v172
	v_cvt_pk_bf16_f32 v102, v102, v103
	v_cvt_pk_bf16_f32 v103, v104, v105
	v_cvt_pk_bf16_f32 v104, v98, v99
	v_cvt_pk_bf16_f32 v105, v100, v101
	s_mov_b64 vcc, s[98:99]
	v_cndmask_b32_dpp v106, v110, v102, vcc quad_perm:[1,0,3,2] row_mask:0xf bank_mask:0xf
	v_cndmask_b32_dpp v107, v111, v103, vcc quad_perm:[1,0,3,2] row_mask:0xf bank_mask:0xf
	v_cndmask_b32_dpp v108, v112, v104, vcc quad_perm:[1,0,3,2] row_mask:0xf bank_mask:0xf
	v_cndmask_b32_dpp v109, v113, v105, vcc quad_perm:[1,0,3,2] row_mask:0xf bank_mask:0xf
	s_mov_b64 vcc, s[10:11]
	v_cndmask_b32_dpp v110, v102, v110, vcc quad_perm:[1,0,3,2] row_mask:0xf bank_mask:0xf
	v_cndmask_b32_dpp v111, v103, v111, vcc quad_perm:[1,0,3,2] row_mask:0xf bank_mask:0xf
	v_cndmask_b32_dpp v112, v104, v112, vcc quad_perm:[1,0,3,2] row_mask:0xf bank_mask:0xf
	v_cndmask_b32_dpp v113, v105, v113, vcc quad_perm:[1,0,3,2] row_mask:0xf bank_mask:0xf
	s_add_u32 s64, s62, 0x8000
	s_addc_u32 s65, s63, 0
	global_store_dwordx4 v251, v[110:113], s[64:65]
	global_store_dwordx4 v163, v[106:109], s[64:65]
	s_waitcnt vmcnt(14)
	v_lshlrev_b32_e32 v172, 16, v222
	v_and_b32_e32 v173, 0xffff0000, v222
	v_pk_add_f32 v[94:95], v[94:95], v[172:173]
	v_lshlrev_b32_e32 v172, 16, v223
	v_and_b32_e32 v173, 0xffff0000, v223
	v_pk_add_f32 v[96:97], v[96:97], v[172:173]
	v_lshlrev_b32_e32 v172, 16, v224
	v_and_b32_e32 v173, 0xffff0000, v224
	v_pk_add_f32 v[90:91], v[90:91], v[172:173]
	v_lshlrev_b32_e32 v172, 16, v225
	v_and_b32_e32 v173, 0xffff0000, v225
	v_pk_add_f32 v[92:93], v[92:93], v[172:173]
	v_mul_f32_e32 v172, v95, v95
	v_mul_f32_e32 v173, v97, v97
	v_mul_f32_e32 v188, v91, v91
	v_mul_f32_e32 v189, v93, v93
	v_fmac_f32_e32 v172, v94, v94
	v_fmac_f32_e32 v173, v96, v96
	v_fmac_f32_e32 v188, v90, v90
	v_fmac_f32_e32 v189, v92, v92
	v_add_f32_e32 v172, v172, v173
	v_add_f32_e32 v188, v188, v189
	v_add_f32_e32 v172, v172, v188
	v_mov_b32_e32 v170, v172
	v_cvt_pk_bf16_f32 v94, v94, v95
	v_cvt_pk_bf16_f32 v95, v96, v97
	v_cvt_pk_bf16_f32 v96, v90, v91
	v_cvt_pk_bf16_f32 v97, v92, v93
	v_lshlrev_b32_e32 v172, 16, v226
	v_and_b32_e32 v173, 0xffff0000, v226
	v_pk_add_f32 v[86:87], v[86:87], v[172:173]
	v_lshlrev_b32_e32 v172, 16, v227
	v_and_b32_e32 v173, 0xffff0000, v227
	v_pk_add_f32 v[88:89], v[88:89], v[172:173]
	v_lshlrev_b32_e32 v172, 16, v228
	v_and_b32_e32 v173, 0xffff0000, v228
	v_pk_add_f32 v[82:83], v[82:83], v[172:173]
	v_lshlrev_b32_e32 v172, 16, v229
	v_and_b32_e32 v173, 0xffff0000, v229
	v_pk_add_f32 v[84:85], v[84:85], v[172:173]
	v_mul_f32_e32 v172, v87, v87
	v_mul_f32_e32 v173, v89, v89
	v_mul_f32_e32 v188, v83, v83
	v_mul_f32_e32 v189, v85, v85
	v_fmac_f32_e32 v172, v86, v86
	v_fmac_f32_e32 v173, v88, v88
	v_fmac_f32_e32 v188, v82, v82
	v_fmac_f32_e32 v189, v84, v84
	v_add_f32_e32 v172, v172, v173
	v_add_f32_e32 v188, v188, v189
	v_add_f32_e32 v172, v172, v188
	v_add_f32_e32 v170, v170, v172
	v_cvt_pk_bf16_f32 v86, v86, v87
	v_cvt_pk_bf16_f32 v87, v88, v89
	v_cvt_pk_bf16_f32 v88, v82, v83
	v_cvt_pk_bf16_f32 v89, v84, v85
	s_mov_b64 vcc, s[98:99]
	v_cndmask_b32_dpp v90, v94, v86, vcc quad_perm:[1,0,3,2] row_mask:0xf bank_mask:0xf
	v_cndmask_b32_dpp v91, v95, v87, vcc quad_perm:[1,0,3,2] row_mask:0xf bank_mask:0xf
	v_cndmask_b32_dpp v92, v96, v88, vcc quad_perm:[1,0,3,2] row_mask:0xf bank_mask:0xf
	v_cndmask_b32_dpp v93, v97, v89, vcc quad_perm:[1,0,3,2] row_mask:0xf bank_mask:0xf
	s_mov_b64 vcc, s[10:11]
	v_cndmask_b32_dpp v94, v86, v94, vcc quad_perm:[1,0,3,2] row_mask:0xf bank_mask:0xf
	v_cndmask_b32_dpp v95, v87, v95, vcc quad_perm:[1,0,3,2] row_mask:0xf bank_mask:0xf
	v_cndmask_b32_dpp v96, v88, v96, vcc quad_perm:[1,0,3,2] row_mask:0xf bank_mask:0xf
	v_cndmask_b32_dpp v97, v89, v97, vcc quad_perm:[1,0,3,2] row_mask:0xf bank_mask:0xf
	s_add_u32 s64, s62, 0x10000
	s_addc_u32 s65, s63, 0
	global_store_dwordx4 v251, v[94:97], s[64:65]
	global_store_dwordx4 v163, v[90:93], s[64:65]
	s_waitcnt vmcnt(14)
; #define LAS __attribute__((address_space(3)))
; __device__ __forceinline__ float bf_lo(unsigned w) { return __uint_as_float(w << 16); }
; __device__ __forceinline__ float bf_hi(unsigned w) { return __uint_as_float(w & 0xffff0000u); }
; __device__ __forceinline__ unsigned cvt_pk_bf16(float lo, float hi) { unsigned r; asm volatile("v_cvt_pk_bf16_f32 %0, %1, %2" : "=v"(r) : "v"(lo), "v"(hi)); return r; }
;     __device__ __forceinline__ void operator()(const f32x4 (&acc)[2][2][4][2], const Unit& u, int wr, int wc, int fr, int fq) const {
;     ...
;             for (int m = 2 * mh; m < 2 * mh + 2; ++m) {
;                 const int rowb = u.pm * BM + ai * HALF + wr * 64 + m * 16; float q = 0.f;
; #pragma unroll
;                 for (int i = 0; i < 2; ++i) *(LAS u32x4*)(sl + (rr + 8 * i) * 144 + cc * 16) = bs[m][i];
; #pragma unroll
;                 for (int bj = 0; bj < 2; ++bj) {
;                     const u32x4 b4 = *(const LAS u32x4*)(sl + fr * 144 + bj * 64 + fq * 16);
;                     const f32x4 a0 = acc[ai][bj][m][0], a1 = acc[ai][bj][m][1];
;                     const float o0 = bf_lo(b4.x) + a0[0], o1 = bf_hi(b4.x) + a0[1], o2 = bf_lo(b4.y) + a0[2], o3 = bf_hi(b4.y) + a0[3];
;                     const float o4 = bf_lo(b4.z) + a1[0], o5 = bf_hi(b4.z) + a1[1], o6 = bf_lo(b4.w) + a1[2], o7 = bf_hi(b4.w) + a1[3];
;                     q += ((o0 * o0 + o1 * o1) + (o2 * o2 + o3 * o3)) + ((o4 * o4 + o5 * o5) + (o6 * o6 + o7 * o7));
;                     u32x4 w; w.x = cvt_pk_bf16(o0, o1); w.y = cvt_pk_bf16(o2, o3); w.z = cvt_pk_bf16(o4, o5); w.w = cvt_pk_bf16(o6, o7);
;                     *(LAS u32x4*)(sl + fr * 144 + bj * 64 + fq * 16) = w;
;                 }
; #pragma unroll
;                 for (int i = 0; i < 2; ++i) { const u32x4 qv = *(const LAS u32x4*)(sl + (rr + 8 * i) * 144 + cc * 16);
;                     *(u32x4*)(xb + (size_t)(rowb + rr + 8 * i) * DM + colw + cc * 8) = qv; }
;                 q += __shfl_xor(q, 16); q += __shfl_xor(q, 32); qs[m] = q;
;             }
;             asm volatile("" ::: "memory");
;             }
;             { const float mine = fq == 0 ? qs[0] : (fq == 1 ? qs[1] : (fq == 2 ? qs[2] : qs[3]));
;               __hip_atomic_fetch_add(ssq + (u.pm * BM + ai * HALF + wr * 64 + 16 * fq + fr), (u64)(mine * 16777216.0f), __ATOMIC_RELAXED, __HIP_MEMORY_SCOPE_AGENT); }
	v_lshlrev_b32_e32 v172, 16, v230
	v_and_b32_e32 v173, 0xffff0000, v230
	v_pk_add_f32 v[78:79], v[78:79], v[172:173]
	v_lshlrev_b32_e32 v172, 16, v231
	v_and_b32_e32 v173, 0xffff0000, v231
	v_pk_add_f32 v[80:81], v[80:81], v[172:173]
	v_lshlrev_b32_e32 v172, 16, v232
	v_and_b32_e32 v173, 0xffff0000, v232
	v_pk_add_f32 v[74:75], v[74:75], v[172:173]
	v_lshlrev_b32_e32 v172, 16, v233
	v_and_b32_e32 v173, 0xffff0000, v233
	v_pk_add_f32 v[76:77], v[76:77], v[172:173]
	v_mul_f32_e32 v172, v79, v79
	v_mul_f32_e32 v173, v81, v81
	v_mul_f32_e32 v188, v75, v75
	v_mul_f32_e32 v189, v77, v77
	v_fmac_f32_e32 v172, v78, v78
	v_fmac_f32_e32 v173, v80, v80
	v_fmac_f32_e32 v188, v74, v74
	v_fmac_f32_e32 v189, v76, v76
	v_add_f32_e32 v172, v172, v173
	v_add_f32_e32 v188, v188, v189
	v_add_f32_e32 v172, v172, v188
	v_mov_b32_e32 v171, v172
	v_cvt_pk_bf16_f32 v78, v78, v79
	v_cvt_pk_bf16_f32 v79, v80, v81
	v_cvt_pk_bf16_f32 v80, v74, v75
	v_cvt_pk_bf16_f32 v81, v76, v77
	v_lshlrev_b32_e32 v172, 16, v234
	v_and_b32_e32 v173, 0xffff0000, v234
	v_pk_add_f32 v[70:71], v[70:71], v[172:173]
	v_lshlrev_b32_e32 v172, 16, v235
	v_and_b32_e32 v173, 0xffff0000, v235
	v_pk_add_f32 v[72:73], v[72:73], v[172:173]
	v_lshlrev_b32_e32 v172, 16, v236
	v_and_b32_e32 v173, 0xffff0000, v236
	v_pk_add_f32 v[66:67], v[66:67], v[172:173]
	v_lshlrev_b32_e32 v172, 16, v237
	v_and_b32_e32 v173, 0xffff0000, v237
	v_pk_add_f32 v[68:69], v[68:69], v[172:173]
	v_mul_f32_e32 v172, v71, v71
	v_mul_f32_e32 v173, v73, v73
	v_mul_f32_e32 v188, v67, v67
	v_mul_f32_e32 v189, v69, v69
	v_fmac_f32_e32 v172, v70, v70
	v_fmac_f32_e32 v173, v72, v72
	v_fmac_f32_e32 v188, v66, v66
	v_fmac_f32_e32 v189, v68, v68
	v_add_f32_e32 v172, v172, v173
	v_add_f32_e32 v188, v188, v189
	v_add_f32_e32 v172, v172, v188
	v_add_f32_e32 v171, v171, v172
	v_cvt_pk_bf16_f32 v70, v70, v71
	v_cvt_pk_bf16_f32 v71, v72, v73
	v_cvt_pk_bf16_f32 v72, v66, v67
	v_cvt_pk_bf16_f32 v73, v68, v69
	s_mov_b64 vcc, s[98:99]
	v_cndmask_b32_dpp v74, v78, v70, vcc quad_perm:[1,0,3,2] row_mask:0xf bank_mask:0xf
	v_cndmask_b32_dpp v75, v79, v71, vcc quad_perm:[1,0,3,2] row_mask:0xf bank_mask:0xf
	v_cndmask_b32_dpp v76, v80, v72, vcc quad_perm:[1,0,3,2] row_mask:0xf bank_mask:0xf
	v_cndmask_b32_dpp v77, v81, v73, vcc quad_perm:[1,0,3,2] row_mask:0xf bank_mask:0xf
	s_mov_b64 vcc, s[10:11]
	v_cndmask_b32_dpp v78, v70, v78, vcc quad_perm:[1,0,3,2] row_mask:0xf bank_mask:0xf
	v_cndmask_b32_dpp v79, v71, v79, vcc quad_perm:[1,0,3,2] row_mask:0xf bank_mask:0xf
	v_cndmask_b32_dpp v80, v72, v80, vcc quad_perm:[1,0,3,2] row_mask:0xf bank_mask:0xf
	v_cndmask_b32_dpp v81, v73, v81, vcc quad_perm:[1,0,3,2] row_mask:0xf bank_mask:0xf
	s_add_u32 s64, s62, 0x18000
	s_addc_u32 s65, s63, 0
	global_store_dwordx4 v251, v[78:81], s[64:65]
	global_store_dwordx4 v163, v[74:77], s[64:65]
	v_xor_b32_e32 v172, 16, v177
	v_lshlrev_b32_e32 v172, 2, v172
	v_xor_b32_e32 v173, 32, v177
	v_lshlrev_b32_e32 v173, 2, v173
	ds_bpermute_b32 v74, v172, v168
	ds_bpermute_b32 v75, v172, v169
	ds_bpermute_b32 v76, v172, v170
	ds_bpermute_b32 v77, v172, v171
	s_waitcnt lgkmcnt(3)
	v_add_f32_e32 v168, v168, v74
	s_waitcnt lgkmcnt(2)
	v_add_f32_e32 v169, v169, v75
	s_waitcnt lgkmcnt(1)
	v_add_f32_e32 v170, v170, v76
	s_waitcnt lgkmcnt(0)
	v_add_f32_e32 v171, v171, v77
	ds_bpermute_b32 v74, v173, v168
	ds_bpermute_b32 v75, v173, v169
	ds_bpermute_b32 v76, v173, v170
	ds_bpermute_b32 v77, v173, v171
	s_waitcnt lgkmcnt(3)
	v_add_f32_e32 v168, v168, v74
	s_waitcnt lgkmcnt(2)
	v_add_f32_e32 v169, v169, v75
	s_waitcnt lgkmcnt(1)
	v_add_f32_e32 v170, v170, v76
	s_waitcnt lgkmcnt(0)
	v_add_f32_e32 v171, v171, v77
	v_bfe_u32 v188, v177, 4, 2
	v_cmp_eq_u32_e32 vcc, 1, v188
	s_nop 1
	v_cndmask_b32_e32 v189, v168, v169, vcc
	v_cmp_eq_u32_e32 vcc, 2, v188
	s_nop 1
	v_cndmask_b32_e32 v189, v189, v170, vcc
	v_cmp_eq_u32_e32 vcc, 3, v188
	s_nop 1
	v_cndmask_b32_e32 v189, v189, v171, vcc
	v_mul_f32_e32 v189, 0x4b800000, v189
	v_trunc_f32_e32 v189, v189
	v_mul_f32_e32 v188, 0x2f800000, v189
	v_floor_f32_e32 v188, v188
	v_fmac_f32_e32 v189, 0xcf800000, v188
	v_cvt_u32_f32_e32 v172, v189
	v_cvt_u32_f32_e32 v173, v188
	s_lshl_b32 s7, s2, 3
	s_add_u32 s100, s42, s7
	s_addc_u32 s101, s43, 0
	v_lshlrev_b32_e32 v250, 3, v177
	global_atomic_add_x2 v250, v[172:173], s[100:101]
	s_waitcnt vmcnt(15)
; #define LAS __attribute__((address_space(3)))
; __device__ __forceinline__ float bf_lo(unsigned w) { return __uint_as_float(w << 16); }
; __device__ __forceinline__ float bf_hi(unsigned w) { return __uint_as_float(w & 0xffff0000u); }
; __device__ __forceinline__ unsigned cvt_pk_bf16(float lo, float hi) { unsigned r; asm volatile("v_cvt_pk_bf16_f32 %0, %1, %2" : "=v"(r) : "v"(lo), "v"(hi)); return r; }
;     __device__ __forceinline__ void operator()(const f32x4 (&acc)[2][2][4][2], const Unit& u, int wr, int wc, int fr, int fq) const {
;     ...
;             for (int m = 2 * mh; m < 2 * mh + 2; ++m) { const int rowb = u.pm * BM + ai * HALF + wr * 64 + m * 16;
; #pragma unroll
;                 for (int i = 0; i < 2; ++i) bs[m][i] = *(const u32x4*)(xb + (size_t)(rowb + rr + 8 * i) * DM + colw + cc * 8); }
; #pragma unroll
;             for (int m = 2 * mh; m < 2 * mh + 2; ++m) {
;                 const int rowb = u.pm * BM + ai * HALF + wr * 64 + m * 16; float q = 0.f;
; #pragma unroll
;                 for (int i = 0; i < 2; ++i) *(LAS u32x4*)(sl + (rr + 8 * i) * 144 + cc * 16) = bs[m][i];
; #pragma unroll
;                 for (int bj = 0; bj < 2; ++bj) {
;                     const u32x4 b4 = *(const LAS u32x4*)(sl + fr * 144 + bj * 64 + fq * 16);
;                     const f32x4 a0 = acc[ai][bj][m][0], a1 = acc[ai][bj][m][1];
;                     const float o0 = bf_lo(b4.x) + a0[0], o1 = bf_hi(b4.x) + a0[1], o2 = bf_lo(b4.y) + a0[2], o3 = bf_hi(b4.y) + a0[3];
;                     const float o4 = bf_lo(b4.z) + a1[0], o5 = bf_hi(b4.z) + a1[1], o6 = bf_lo(b4.w) + a1[2], o7 = bf_hi(b4.w) + a1[3];
;                     q += ((o0 * o0 + o1 * o1) + (o2 * o2 + o3 * o3)) + ((o4 * o4 + o5 * o5) + (o6 * o6 + o7 * o7));
;                     u32x4 w; w.x = cvt_pk_bf16(o0, o1); w.y = cvt_pk_bf16(o2, o3); w.z = cvt_pk_bf16(o4, o5); w.w = cvt_pk_bf16(o6, o7);
;                     *(LAS u32x4*)(sl + fr * 144 + bj * 64 + fq * 16) = w;
;                 }
; #pragma unroll
;                 for (int i = 0; i < 2; ++i) { const u32x4 qv = *(const LAS u32x4*)(sl + (rr + 8 * i) * 144 + cc * 16);
;                     *(u32x4*)(xb + (size_t)(rowb + rr + 8 * i) * DM + colw + cc * 8) = qv; }
	v_lshlrev_b32_e32 v172, 16, v238
	v_and_b32_e32 v173, 0xffff0000, v238
	v_pk_add_f32 v[62:63], v[62:63], v[172:173]
	v_lshlrev_b32_e32 v172, 16, v239
	v_and_b32_e32 v173, 0xffff0000, v239
	v_pk_add_f32 v[64:65], v[64:65], v[172:173]
	v_lshlrev_b32_e32 v172, 16, v240
	v_and_b32_e32 v173, 0xffff0000, v240
	v_pk_add_f32 v[58:59], v[58:59], v[172:173]
	v_lshlrev_b32_e32 v172, 16, v241
	v_and_b32_e32 v173, 0xffff0000, v241
	v_pk_add_f32 v[60:61], v[60:61], v[172:173]
	v_mul_f32_e32 v172, v63, v63
	v_mul_f32_e32 v173, v65, v65
	v_mul_f32_e32 v188, v59, v59
	v_mul_f32_e32 v189, v61, v61
	v_fmac_f32_e32 v172, v62, v62
	v_fmac_f32_e32 v173, v64, v64
	v_fmac_f32_e32 v188, v58, v58
	v_fmac_f32_e32 v189, v60, v60
	v_add_f32_e32 v172, v172, v173
	v_add_f32_e32 v188, v188, v189
	v_add_f32_e32 v172, v172, v188
	v_mov_b32_e32 v168, v172
	v_cvt_pk_bf16_f32 v62, v62, v63
	v_cvt_pk_bf16_f32 v63, v64, v65
	v_cvt_pk_bf16_f32 v64, v58, v59
	v_cvt_pk_bf16_f32 v65, v60, v61
	v_lshlrev_b32_e32 v172, 16, v242
	v_and_b32_e32 v173, 0xffff0000, v242
	v_pk_add_f32 v[54:55], v[54:55], v[172:173]
	v_lshlrev_b32_e32 v172, 16, v243
	v_and_b32_e32 v173, 0xffff0000, v243
	v_pk_add_f32 v[56:57], v[56:57], v[172:173]
	v_lshlrev_b32_e32 v172, 16, v244
	v_and_b32_e32 v173, 0xffff0000, v244
	v_pk_add_f32 v[50:51], v[50:51], v[172:173]
	v_lshlrev_b32_e32 v172, 16, v245
	v_and_b32_e32 v173, 0xffff0000, v245
	v_pk_add_f32 v[52:53], v[52:53], v[172:173]
	v_mul_f32_e32 v172, v55, v55
	v_mul_f32_e32 v173, v57, v57
	v_mul_f32_e32 v188, v51, v51
	v_mul_f32_e32 v189, v53, v53
	v_fmac_f32_e32 v172, v54, v54
	v_fmac_f32_e32 v173, v56, v56
	v_fmac_f32_e32 v188, v50, v50
	v_fmac_f32_e32 v189, v52, v52
	v_add_f32_e32 v172, v172, v173
	v_add_f32_e32 v188, v188, v189
	v_add_f32_e32 v172, v172, v188
	v_add_f32_e32 v168, v168, v172
	v_cvt_pk_bf16_f32 v54, v54, v55
	v_cvt_pk_bf16_f32 v55, v56, v57
	v_cvt_pk_bf16_f32 v56, v50, v51
	v_cvt_pk_bf16_f32 v57, v52, v53
	s_mov_b64 vcc, s[98:99]
	v_cndmask_b32_dpp v58, v62, v54, vcc quad_perm:[1,0,3,2] row_mask:0xf bank_mask:0xf
	v_cndmask_b32_dpp v59, v63, v55, vcc quad_perm:[1,0,3,2] row_mask:0xf bank_mask:0xf
	v_cndmask_b32_dpp v60, v64, v56, vcc quad_perm:[1,0,3,2] row_mask:0xf bank_mask:0xf
	v_cndmask_b32_dpp v61, v65, v57, vcc quad_perm:[1,0,3,2] row_mask:0xf bank_mask:0xf
	s_mov_b64 vcc, s[10:11]
	v_cndmask_b32_dpp v62, v54, v62, vcc quad_perm:[1,0,3,2] row_mask:0xf bank_mask:0xf
	v_cndmask_b32_dpp v63, v55, v63, vcc quad_perm:[1,0,3,2] row_mask:0xf bank_mask:0xf
	v_cndmask_b32_dpp v64, v56, v64, vcc quad_perm:[1,0,3,2] row_mask:0xf bank_mask:0xf
	v_cndmask_b32_dpp v65, v57, v65, vcc quad_perm:[1,0,3,2] row_mask:0xf bank_mask:0xf
	s_add_u32 s64, s62, 0x40000
	s_addc_u32 s65, s63, 0
	global_store_dwordx4 v251, v[62:65], s[64:65]
	global_store_dwordx4 v163, v[58:61], s[64:65]
	s_waitcnt vmcnt(15)
	v_lshlrev_b32_e32 v172, 16, v246
	v_and_b32_e32 v173, 0xffff0000, v246
	v_pk_add_f32 v[46:47], v[46:47], v[172:173]
	v_lshlrev_b32_e32 v172, 16, v247
	v_and_b32_e32 v173, 0xffff0000, v247
	v_pk_add_f32 v[48:49], v[48:49], v[172:173]
	v_lshlrev_b32_e32 v172, 16, v248
	v_and_b32_e32 v173, 0xffff0000, v248
	v_pk_add_f32 v[42:43], v[42:43], v[172:173]
	v_lshlrev_b32_e32 v172, 16, v249
	v_and_b32_e32 v173, 0xffff0000, v249
	v_pk_add_f32 v[44:45], v[44:45], v[172:173]
	v_mul_f32_e32 v172, v47, v47
	v_mul_f32_e32 v173, v49, v49
	v_mul_f32_e32 v188, v43, v43
	v_mul_f32_e32 v189, v45, v45
	v_fmac_f32_e32 v172, v46, v46
	v_fmac_f32_e32 v173, v48, v48
	v_fmac_f32_e32 v188, v42, v42
	v_fmac_f32_e32 v189, v44, v44
	v_add_f32_e32 v172, v172, v173
	v_add_f32_e32 v188, v188, v189
	v_add_f32_e32 v172, v172, v188
	v_mov_b32_e32 v169, v172
	v_cvt_pk_bf16_f32 v46, v46, v47
	v_cvt_pk_bf16_f32 v47, v48, v49
	v_cvt_pk_bf16_f32 v48, v42, v43
	v_cvt_pk_bf16_f32 v49, v44, v45
	v_lshlrev_b32_e32 v172, 16, v198
	v_and_b32_e32 v173, 0xffff0000, v198
	v_pk_add_f32 v[38:39], v[38:39], v[172:173]
	v_lshlrev_b32_e32 v172, 16, v199
	v_and_b32_e32 v173, 0xffff0000, v199
	v_pk_add_f32 v[40:41], v[40:41], v[172:173]
	v_lshlrev_b32_e32 v172, 16, v200
	v_and_b32_e32 v173, 0xffff0000, v200
	v_pk_add_f32 v[34:35], v[34:35], v[172:173]
	v_lshlrev_b32_e32 v172, 16, v201
	v_and_b32_e32 v173, 0xffff0000, v201
	v_pk_add_f32 v[36:37], v[36:37], v[172:173]
	v_mul_f32_e32 v172, v39, v39
	v_mul_f32_e32 v173, v41, v41
	v_mul_f32_e32 v188, v35, v35
	v_mul_f32_e32 v189, v37, v37
	v_fmac_f32_e32 v172, v38, v38
	v_fmac_f32_e32 v173, v40, v40
	v_fmac_f32_e32 v188, v34, v34
	v_fmac_f32_e32 v189, v36, v36
	v_add_f32_e32 v172, v172, v173
	v_add_f32_e32 v188, v188, v189
	v_add_f32_e32 v172, v172, v188
	v_add_f32_e32 v169, v169, v172
	v_cvt_pk_bf16_f32 v38, v38, v39
	v_cvt_pk_bf16_f32 v39, v40, v41
	v_cvt_pk_bf16_f32 v40, v34, v35
	v_cvt_pk_bf16_f32 v41, v36, v37
	s_mov_b64 vcc, s[98:99]
	v_cndmask_b32_dpp v42, v46, v38, vcc quad_perm:[1,0,3,2] row_mask:0xf bank_mask:0xf
	v_cndmask_b32_dpp v43, v47, v39, vcc quad_perm:[1,0,3,2] row_mask:0xf bank_mask:0xf
	v_cndmask_b32_dpp v44, v48, v40, vcc quad_perm:[1,0,3,2] row_mask:0xf bank_mask:0xf
	v_cndmask_b32_dpp v45, v49, v41, vcc quad_perm:[1,0,3,2] row_mask:0xf bank_mask:0xf
	s_mov_b64 vcc, s[10:11]
	v_cndmask_b32_dpp v46, v38, v46, vcc quad_perm:[1,0,3,2] row_mask:0xf bank_mask:0xf
	v_cndmask_b32_dpp v47, v39, v47, vcc quad_perm:[1,0,3,2] row_mask:0xf bank_mask:0xf
	v_cndmask_b32_dpp v48, v40, v48, vcc quad_perm:[1,0,3,2] row_mask:0xf bank_mask:0xf
	v_cndmask_b32_dpp v49, v41, v49, vcc quad_perm:[1,0,3,2] row_mask:0xf bank_mask:0xf
	s_add_u32 s64, s62, 0x48000
	s_addc_u32 s65, s63, 0
	global_store_dwordx4 v251, v[46:49], s[64:65]
	global_store_dwordx4 v163, v[42:45], s[64:65]
	s_waitcnt vmcnt(15)
; #define LAS __attribute__((address_space(3)))
; __device__ __forceinline__ float bf_lo(unsigned w) { return __uint_as_float(w << 16); }
; __device__ __forceinline__ float bf_hi(unsigned w) { return __uint_as_float(w & 0xffff0000u); }
; __device__ __forceinline__ unsigned cvt_pk_bf16(float lo, float hi) { unsigned r; asm volatile("v_cvt_pk_bf16_f32 %0, %1, %2" : "=v"(r) : "v"(lo), "v"(hi)); return r; }
;     __device__ __forceinline__ void operator()(const f32x4 (&acc)[2][2][4][2], const Unit& u, int wr, int wc, int fr, int fq) const {
;     ...
;             for (int m = 2 * mh; m < 2 * mh + 2; ++m) {
;                 const int rowb = u.pm * BM + ai * HALF + wr * 64 + m * 16; float q = 0.f;
; #pragma unroll
;                 for (int i = 0; i < 2; ++i) *(LAS u32x4*)(sl + (rr + 8 * i) * 144 + cc * 16) = bs[m][i];
; #pragma unroll
;                 for (int bj = 0; bj < 2; ++bj) {
;                     const u32x4 b4 = *(const LAS u32x4*)(sl + fr * 144 + bj * 64 + fq * 16);
;                     const f32x4 a0 = acc[ai][bj][m][0], a1 = acc[ai][bj][m][1];
;                     const float o0 = bf_lo(b4.x) + a0[0], o1 = bf_hi(b4.x) + a0[1], o2 = bf_lo(b4.y) + a0[2], o3 = bf_hi(b4.y) + a0[3];
;                     const float o4 = bf_lo(b4.z) + a1[0], o5 = bf_hi(b4.z) + a1[1], o6 = bf_lo(b4.w) + a1[2], o7 = bf_hi(b4.w) + a1[3];
;                     q += ((o0 * o0 + o1 * o1) + (o2 * o2 + o3 * o3)) + ((o4 * o4 + o5 * o5) + (o6 * o6 + o7 * o7));
;                     u32x4 w; w.x = cvt_pk_bf16(o0, o1); w.y = cvt_pk_bf16(o2, o3); w.z = cvt_pk_bf16(o4, o5); w.w = cvt_pk_bf16(o6, o7);
;                     *(LAS u32x4*)(sl + fr * 144 + bj * 64 + fq * 16) = w;
;                 }
; #pragma unroll
;                 for (int i = 0; i < 2; ++i) { const u32x4 qv = *(const LAS u32x4*)(sl + (rr + 8 * i) * 144 + cc * 16);
;                     *(u32x4*)(xb + (size_t)(rowb + rr + 8 * i) * DM + colw + cc * 8) = qv; }
	v_lshlrev_b32_e32 v172, 16, v202
	v_and_b32_e32 v173, 0xffff0000, v202
	v_pk_add_f32 v[30:31], v[30:31], v[172:173]
	v_lshlrev_b32_e32 v172, 16, v203
	v_and_b32_e32 v173, 0xffff0000, v203
	v_pk_add_f32 v[32:33], v[32:33], v[172:173]
	v_lshlrev_b32_e32 v172, 16, v204
	v_and_b32_e32 v173, 0xffff0000, v204
	v_pk_add_f32 v[26:27], v[26:27], v[172:173]
	v_lshlrev_b32_e32 v172, 16, v205
	v_and_b32_e32 v173, 0xffff0000, v205
	v_pk_add_f32 v[28:29], v[28:29], v[172:173]
	v_mul_f32_e32 v172, v31, v31
	v_mul_f32_e32 v173, v33, v33
	v_mul_f32_e32 v188, v27, v27
	v_mul_f32_e32 v189, v29, v29
	v_fmac_f32_e32 v172, v30, v30
	v_fmac_f32_e32 v173, v32, v32
	v_fmac_f32_e32 v188, v26, v26
	v_fmac_f32_e32 v189, v28, v28
	v_add_f32_e32 v172, v172, v173
	v_add_f32_e32 v188, v188, v189
	v_add_f32_e32 v172, v172, v188
	v_mov_b32_e32 v170, v172
	v_cvt_pk_bf16_f32 v30, v30, v31
	v_cvt_pk_bf16_f32 v31, v32, v33
	v_cvt_pk_bf16_f32 v32, v26, v27
	v_cvt_pk_bf16_f32 v33, v28, v29
	v_lshlrev_b32_e32 v172, 16, v130
	v_and_b32_e32 v173, 0xffff0000, v130
	v_pk_add_f32 v[22:23], v[22:23], v[172:173]
	v_lshlrev_b32_e32 v172, 16, v131
	v_and_b32_e32 v173, 0xffff0000, v131
	v_pk_add_f32 v[24:25], v[24:25], v[172:173]
	v_lshlrev_b32_e32 v172, 16, v132
	v_and_b32_e32 v173, 0xffff0000, v132
	v_pk_add_f32 v[18:19], v[18:19], v[172:173]
	v_lshlrev_b32_e32 v172, 16, v133
	v_and_b32_e32 v173, 0xffff0000, v133
	v_pk_add_f32 v[20:21], v[20:21], v[172:173]
	v_mul_f32_e32 v172, v23, v23
	v_mul_f32_e32 v173, v25, v25
	v_mul_f32_e32 v188, v19, v19
	v_mul_f32_e32 v189, v21, v21
	v_fmac_f32_e32 v172, v22, v22
	v_fmac_f32_e32 v173, v24, v24
	v_fmac_f32_e32 v188, v18, v18
	v_fmac_f32_e32 v189, v20, v20
	v_add_f32_e32 v172, v172, v173
	v_add_f32_e32 v188, v188, v189
	v_add_f32_e32 v172, v172, v188
	v_add_f32_e32 v170, v170, v172
	v_cvt_pk_bf16_f32 v22, v22, v23
	v_cvt_pk_bf16_f32 v23, v24, v25
	v_cvt_pk_bf16_f32 v24, v18, v19
	v_cvt_pk_bf16_f32 v25, v20, v21
	s_mov_b64 vcc, s[98:99]
	v_cndmask_b32_dpp v26, v30, v22, vcc quad_perm:[1,0,3,2] row_mask:0xf bank_mask:0xf
	v_cndmask_b32_dpp v27, v31, v23, vcc quad_perm:[1,0,3,2] row_mask:0xf bank_mask:0xf
	v_cndmask_b32_dpp v28, v32, v24, vcc quad_perm:[1,0,3,2] row_mask:0xf bank_mask:0xf
	v_cndmask_b32_dpp v29, v33, v25, vcc quad_perm:[1,0,3,2] row_mask:0xf bank_mask:0xf
	s_mov_b64 vcc, s[10:11]
	v_cndmask_b32_dpp v30, v22, v30, vcc quad_perm:[1,0,3,2] row_mask:0xf bank_mask:0xf
	v_cndmask_b32_dpp v31, v23, v31, vcc quad_perm:[1,0,3,2] row_mask:0xf bank_mask:0xf
	v_cndmask_b32_dpp v32, v24, v32, vcc quad_perm:[1,0,3,2] row_mask:0xf bank_mask:0xf
	v_cndmask_b32_dpp v33, v25, v33, vcc quad_perm:[1,0,3,2] row_mask:0xf bank_mask:0xf
	s_add_u32 s64, s62, 0x50000
	s_addc_u32 s65, s63, 0
	global_store_dwordx4 v251, v[30:33], s[64:65]
	global_store_dwordx4 v163, v[26:29], s[64:65]
	s_waitcnt vmcnt(15)
; #define LAS __attribute__((address_space(3)))
; __device__ __forceinline__ float bf_lo(unsigned w) { return __uint_as_float(w << 16); }
; __device__ __forceinline__ float bf_hi(unsigned w) { return __uint_as_float(w & 0xffff0000u); }
;     __device__ __forceinline__ void operator()(const f32x4 (&acc)[2][2][4][2], const Unit& u, int wr, int wc, int fr, int fq) const {
;     ...
;             for (int m = 2 * mh; m < 2 * mh + 2; ++m) {
;                 const int rowb = u.pm * BM + ai * HALF + wr * 64 + m * 16; float q = 0.f;
; #pragma unroll
;                 for (int i = 0; i < 2; ++i) *(LAS u32x4*)(sl + (rr + 8 * i) * 144 + cc * 16) = bs[m][i];
; #pragma unroll
;                 for (int bj = 0; bj < 2; ++bj) {
;                     const u32x4 b4 = *(const LAS u32x4*)(sl + fr * 144 + bj * 64 + fq * 16);
;                     const f32x4 a0 = acc[ai][bj][m][0], a1 = acc[ai][bj][m][1];
;                     const float o0 = bf_lo(b4.x) + a0[0], o1 = bf_hi(b4.x) + a0[1], o2 = bf_lo(b4.y) + a0[2], o3 = bf_hi(b4.y) + a0[3];
;                     const float o4 = bf_lo(b4.z) + a1[0], o5 = bf_hi(b4.z) + a1[1], o6 = bf_lo(b4.w) + a1[2], o7 = bf_hi(b4.w) + a1[3];
;                     q += ((o0 * o0 + o1 * o1) + (o2 * o2 + o3 * o3)) + ((o4 * o4 + o5 * o5) + (o6 * o6 + o7 * o7));
;                     u32x4 w; w.x = cvt_pk_bf16(o0, o1); w.y = cvt_pk_bf16(o2, o3); w.z = cvt_pk_bf16(o4, o5); w.w = cvt_pk_bf16(o6, o7);
;                     *(LAS u32x4*)(sl + fr * 144 + bj * 64 + fq * 16) = w;
;                 }
; #pragma unroll
;                 for (int i = 0; i < 2; ++i) { const u32x4 qv = *(const LAS u32x4*)(sl + (rr + 8 * i) * 144 + cc * 16);
;                     *(u32x4*)(xb + (size_t)(rowb + rr + 8 * i) * DM + colw + cc * 8) = qv; }
;                 q += __shfl_xor(q, 16); q += __shfl_xor(q, 32); qs[m] = q;
;             }
;             asm volatile("" ::: "memory");
;             }
;             { const float mine = fq == 0 ? qs[0] : (fq == 1 ? qs[1] : (fq == 2 ? qs[2] : qs[3]));
;               __hip_atomic_fetch_add(ssq + (u.pm * BM + ai * HALF + wr * 64 + 16 * fq + fr), (u64)(mine * 16777216.0f), __ATOMIC_RELAXED, __HIP_MEMORY_SCOPE_AGENT); }
;             asm volatile("" ::: "memory");
;         }
;     }
	v_lshlrev_b32_e32 v172, 16, v134
	v_and_b32_e32 v173, 0xffff0000, v134
	v_pk_add_f32 v[14:15], v[14:15], v[172:173]
	v_lshlrev_b32_e32 v172, 16, v135
	v_and_b32_e32 v173, 0xffff0000, v135
	v_pk_add_f32 v[16:17], v[16:17], v[172:173]
	v_lshlrev_b32_e32 v172, 16, v136
	v_and_b32_e32 v173, 0xffff0000, v136
	v_pk_add_f32 v[10:11], v[10:11], v[172:173]
	v_lshlrev_b32_e32 v172, 16, v137
	v_and_b32_e32 v173, 0xffff0000, v137
	v_pk_add_f32 v[12:13], v[12:13], v[172:173]
	v_mul_f32_e32 v172, v15, v15
	v_mul_f32_e32 v173, v17, v17
	v_mul_f32_e32 v188, v11, v11
	v_mul_f32_e32 v189, v13, v13
	v_fmac_f32_e32 v172, v14, v14
	v_fmac_f32_e32 v173, v16, v16
	v_fmac_f32_e32 v188, v10, v10
	v_fmac_f32_e32 v189, v12, v12
	v_add_f32_e32 v172, v172, v173
	v_add_f32_e32 v188, v188, v189
	v_add_f32_e32 v172, v172, v188
	v_mov_b32_e32 v171, v172
	v_cvt_pk_bf16_f32 v14, v14, v15
	v_cvt_pk_bf16_f32 v15, v16, v17
	v_cvt_pk_bf16_f32 v16, v10, v11
	v_cvt_pk_bf16_f32 v17, v12, v13
	v_lshlrev_b32_e32 v172, 16, v164
	v_and_b32_e32 v173, 0xffff0000, v164
	v_pk_add_f32 v[6:7], v[6:7], v[172:173]
	v_lshlrev_b32_e32 v172, 16, v165
	v_and_b32_e32 v173, 0xffff0000, v165
	v_pk_add_f32 v[8:9], v[8:9], v[172:173]
	v_lshlrev_b32_e32 v172, 16, v166
	v_and_b32_e32 v173, 0xffff0000, v166
	v_pk_add_f32 v[2:3], v[2:3], v[172:173]
	v_lshlrev_b32_e32 v172, 16, v167
	v_and_b32_e32 v173, 0xffff0000, v167
	v_pk_add_f32 v[4:5], v[4:5], v[172:173]
	v_mul_f32_e32 v172, v7, v7
	v_mul_f32_e32 v173, v9, v9
	v_mul_f32_e32 v188, v3, v3
	v_mul_f32_e32 v189, v5, v5
	v_fmac_f32_e32 v172, v6, v6
	v_fmac_f32_e32 v173, v8, v8
	v_fmac_f32_e32 v188, v2, v2
	v_fmac_f32_e32 v189, v4, v4
	v_add_f32_e32 v172, v172, v173
	v_add_f32_e32 v188, v188, v189
	v_add_f32_e32 v172, v172, v188
	v_add_f32_e32 v171, v171, v172
	v_cvt_pk_bf16_f32 v6, v6, v7
	v_cvt_pk_bf16_f32 v7, v8, v9
	v_cvt_pk_bf16_f32 v8, v2, v3
	v_cvt_pk_bf16_f32 v9, v4, v5
	s_mov_b64 vcc, s[98:99]
	v_cndmask_b32_dpp v10, v14, v6, vcc quad_perm:[1,0,3,2] row_mask:0xf bank_mask:0xf
	v_cndmask_b32_dpp v11, v15, v7, vcc quad_perm:[1,0,3,2] row_mask:0xf bank_mask:0xf
	v_cndmask_b32_dpp v12, v16, v8, vcc quad_perm:[1,0,3,2] row_mask:0xf bank_mask:0xf
	v_cndmask_b32_dpp v13, v17, v9, vcc quad_perm:[1,0,3,2] row_mask:0xf bank_mask:0xf
	s_mov_b64 vcc, s[10:11]
	v_cndmask_b32_dpp v14, v6, v14, vcc quad_perm:[1,0,3,2] row_mask:0xf bank_mask:0xf
	v_cndmask_b32_dpp v15, v7, v15, vcc quad_perm:[1,0,3,2] row_mask:0xf bank_mask:0xf
	v_cndmask_b32_dpp v16, v8, v16, vcc quad_perm:[1,0,3,2] row_mask:0xf bank_mask:0xf
	v_cndmask_b32_dpp v17, v9, v17, vcc quad_perm:[1,0,3,2] row_mask:0xf bank_mask:0xf
	s_add_u32 s64, s62, 0x58000
	s_addc_u32 s65, s63, 0
	global_store_dwordx4 v251, v[14:17], s[64:65]
	global_store_dwordx4 v163, v[10:13], s[64:65]
	v_xor_b32_e32 v172, 16, v177
	v_lshlrev_b32_e32 v172, 2, v172
	v_xor_b32_e32 v173, 32, v177
	v_lshlrev_b32_e32 v173, 2, v173
	ds_bpermute_b32 v10, v172, v168
	ds_bpermute_b32 v11, v172, v169
	ds_bpermute_b32 v12, v172, v170
	ds_bpermute_b32 v13, v172, v171
	s_waitcnt lgkmcnt(3)
	v_add_f32_e32 v168, v168, v10
	s_waitcnt lgkmcnt(2)
	v_add_f32_e32 v169, v169, v11
	s_waitcnt lgkmcnt(1)
	v_add_f32_e32 v170, v170, v12
	s_waitcnt lgkmcnt(0)
	v_add_f32_e32 v171, v171, v13
	ds_bpermute_b32 v10, v173, v168
	ds_bpermute_b32 v11, v173, v169
	ds_bpermute_b32 v12, v173, v170
	ds_bpermute_b32 v13, v173, v171
	s_waitcnt lgkmcnt(3)
	v_add_f32_e32 v168, v168, v10
	s_waitcnt lgkmcnt(2)
	v_add_f32_e32 v169, v169, v11
	s_waitcnt lgkmcnt(1)
	v_add_f32_e32 v170, v170, v12
	s_waitcnt lgkmcnt(0)
	v_add_f32_e32 v171, v171, v13
	v_bfe_u32 v188, v177, 4, 2
	v_cmp_eq_u32_e32 vcc, 1, v188
	s_nop 1
	v_cndmask_b32_e32 v189, v168, v169, vcc
	v_cmp_eq_u32_e32 vcc, 2, v188
	s_nop 1
	v_cndmask_b32_e32 v189, v189, v170, vcc
	v_cmp_eq_u32_e32 vcc, 3, v188
	s_nop 1
	v_cndmask_b32_e32 v189, v189, v171, vcc
	v_mul_f32_e32 v189, 0x4b800000, v189
	v_trunc_f32_e32 v189, v189
	v_mul_f32_e32 v188, 0x2f800000, v189
	v_floor_f32_e32 v188, v188
	v_fmac_f32_e32 v189, 0xcf800000, v188
	v_cvt_u32_f32_e32 v172, v189
	v_cvt_u32_f32_e32 v173, v188
	s_andn2_b64 vcc, exec, s[38:39]
	s_mov_b64 s[26:27], -1
	global_atomic_add_x2 v250, v[172:173], s[100:101] offset:1024
	s_cbranch_vccnz .LBB0_580
	s_andn2_b64 vcc, exec, s[28:29]
	s_cbranch_vccnz .LBB0_579
	s_barrier
	s_branch .LBB0_579
